# adds phase-4 first-layer epilogue: f32 residual-input loads prefetched half a block ahead (counted vmcnt) instead of 16 serial round trips
# baseline (speedup 1.0000x reference)
; __device__ __forceinline__ float bf_lo(unsigned w) { return __uint_as_float(w << 16); }
; __device__ __forceinline__ float bf_hi(unsigned w) { return __uint_as_float(w & 0xffff0000u); }
; __device__ __forceinline__ float shflx(float v, int k, int lane) { return __int_as_float(__builtin_amdgcn_ds_bpermute((lane ^ k) << 2, __float_as_int(v))); }
; __device__ __forceinline__ u32x4 pack8(const f32x4 a, const f32x4 b) { u32x4 w; w.x = cvt_pk_bf16(a[0], a[1]); w.y = cvt_pk_bf16(a[2], a[3]); w.z = cvt_pk_bf16(b[0], b[1]); w.w = cvt_pk_bf16(b[2], b[3]); return w; }
;     __device__ __forceinline__ void operator()(const f32x4 (&acc)[2][2][4][2], const pg8::Unit& u, int wr, int wc, int fr, int fq, LAS unsigned char* lds, int par) const {
;     ...
;                 for (int bj = 0; bj < 2; ++bj) {
;                     f32x4 r0, r1;
;                     if (prev) {
;                         const u32x4 w = *(const u32x4*)(tb + ro + bj * 8);
;                         r0 = (f32x4){bf_lo(w.x), bf_hi(w.x), bf_lo(w.y), bf_hi(w.y)}; r1 = (f32x4){bf_lo(w.z), bf_hi(w.z), bf_lo(w.w), bf_hi(w.w)};
;                         r0 = (r0 - mu) * rstd * gg[2 * bj] + bb[2 * bj]; r1 = (r1 - mu) * rstd * gg[2 * bj + 1] + bb[2 * bj + 1];
;                     } else { r0 = *(const f32x4*)(xin + ro + bj * 8); r1 = *(const f32x4*)(xin + ro + bj * 8 + 4); }
;                     const f32x4 t0 = r0 * ALPHA + acc[ai][bj][m][0], t1 = r1 * ALPHA + acc[ai][bj][m][1];
;                     if (xout != nullptr) { *(f32x4*)(xout + ro + bj * 8) = t0; *(f32x4*)(xout + ro + bj * 8 + 4) = t1; }
;                     const u32x4 pw = pack8(t0, t1);
;                     *(u32x4*)(tb + ro + bj * 8) = pw;
;                     const float a0 = bf_lo(pw.x), a1 = bf_hi(pw.x), a2 = bf_lo(pw.y), a3 = bf_hi(pw.y), a4 = bf_lo(pw.z), a5 = bf_hi(pw.z), a6 = bf_lo(pw.w), a7 = bf_hi(pw.w);
;                     s1 += ((a0 + a1) + (a2 + a3)) + ((a4 + a5) + (a6 + a7));
;                     s2 += ((a0 * a0 + a1 * a1) + (a2 * a2 + a3 * a3)) + ((a4 * a4 + a5 * a5) + (a6 * a6 + a7 * a7));
;                 }
;                 s1 += shflx(s1, 16, fr + 16 * fq); s1 += shflx(s1, 32, fr + 16 * fq); s2 += shflx(s2, 16, fr + 16 * fq); s2 += shflx(s2, 32, fr + 16 * fq);
;                 if (fq == 0) { float* sp = stats_out + ((size_t)row * 32 + u.pn * 4 + wc) * 2; sp[0] = s1; sp[1] = s2; }
.LBB0_323:
	s_andn2_b64 vcc, exec, s[38:39]
	v_lshl_add_u64 v[200:201], v[200:201], 2, s[12:13]
	s_cbranch_vccnz .LBB0_325
	v_lshlrev_b32_e32 v238, 13, v192
	v_lshl_add_u32 v238, v190, 2, v238
	global_load_dwordx4 v[222:225], v238, s[12:13] offset:16
	global_load_dwordx4 v[226:229], v238, s[12:13]
	global_load_dwordx4 v[230:233], v238, s[12:13] offset:48
	global_load_dwordx4 v[234:237], v238, s[12:13] offset:32
	s_waitcnt vmcnt(0)
	v_mov_b32_e32 v162, v222
	v_mov_b32_e32 v163, v223
	v_mov_b32_e32 v164, v224
	v_mov_b32_e32 v165, v225
	v_mov_b32_e32 v166, v226
	v_mov_b32_e32 v167, v227
	v_mov_b32_e32 v168, v228
	v_mov_b32_e32 v169, v229
.LBB0_325:
	v_pk_fma_f32 v[160:161], v[168:169], s[72:73], v[160:161] op_sel_hi:[1,0,1]
	v_pk_fma_f32 v[158:159], v[166:167], s[72:73], v[158:159] op_sel_hi:[1,0,1]
	v_pk_fma_f32 v[164:165], v[164:165], s[72:73], v[156:157] op_sel_hi:[1,0,1]
	v_pk_fma_f32 v[156:157], v[162:163], s[72:73], v[154:155] op_sel_hi:[1,0,1]
	s_and_b64 vcc, exec, s[6:7]
	s_mov_b64 s[38:39], -1
	v_cvt_pk_bf16_f32 v154, v158, v159
	v_cvt_pk_bf16_f32 v155, v160, v161
	v_cvt_pk_bf16_f32 v156, v156, v157
	v_cvt_pk_bf16_f32 v157, v164, v165
	flat_store_dwordx4 v[194:195], v[154:157]
	s_cbranch_vccnz .LBB0_327
	flat_load_dwordx4 v[158:161], v[194:195] offset:16
	v_mov_b32_e32 v162, v198
	v_mov_b32_e32 v163, v198
	s_mov_b64 s[38:39], 0
	s_waitcnt vmcnt(0) lgkmcnt(0)
	v_lshlrev_b32_e32 v164, 16, v158
	v_and_b32_e32 v165, 0xffff0000, v158
	v_lshlrev_b32_e32 v158, 16, v159
	v_and_b32_e32 v159, 0xffff0000, v159
	v_lshlrev_b32_e32 v166, 16, v160
	v_and_b32_e32 v167, 0xffff0000, v160
	v_lshlrev_b32_e32 v168, 16, v161
	v_and_b32_e32 v169, 0xffff0000, v161
	v_sub_f32_e32 v159, v159, v196
	v_sub_f32_e32 v158, v158, v196
	v_sub_f32_e32 v161, v165, v196
	v_sub_f32_e32 v160, v164, v196
	v_sub_f32_e32 v165, v169, v196
	v_sub_f32_e32 v164, v168, v196
	v_sub_f32_e32 v167, v167, v196
	v_sub_f32_e32 v166, v166, v196
	v_pk_mul_f32 v[160:161], v[198:199], v[160:161]
	v_pk_mul_f32 v[158:159], v[162:163], v[158:159]
	v_pk_mul_f32 v[166:167], v[198:199], v[166:167]
	v_pk_mul_f32 v[168:169], v[162:163], v[164:165]
	v_pk_fma_f32 v[164:165], v[44:45], v[158:159], v[48:49]
	v_pk_fma_f32 v[162:163], v[42:43], v[160:161], v[46:47]
	v_pk_fma_f32 v[160:161], v[36:37], v[168:169], v[40:41]
	v_pk_fma_f32 v[158:159], v[34:35], v[166:167], v[38:39]
.LBB0_327:
	s_andn2_b64 vcc, exec, s[38:39]
	s_cbranch_vccnz .LBB0_329
	v_mov_b32_e32 v158, v230
	v_mov_b32_e32 v159, v231
	v_mov_b32_e32 v160, v232
	v_mov_b32_e32 v161, v233
	v_mov_b32_e32 v162, v234
	v_mov_b32_e32 v163, v235
	v_mov_b32_e32 v164, v236
	v_mov_b32_e32 v165, v237
	v_add_u32_e32 v238, 0x20000, v238
	global_load_dwordx4 v[222:225], v238, s[12:13] offset:16
	global_load_dwordx4 v[226:229], v238, s[12:13]
	global_load_dwordx4 v[230:233], v238, s[12:13] offset:48
	global_load_dwordx4 v[234:237], v238, s[12:13] offset:32
.LBB0_329:
	v_and_b32_e32 v173, 16, v154
	v_and_b32_e32 v172, 0xffff0000, v154
	v_lshlrev_b32_e32 v177, 16, v155
	v_lshlrev_b32_e32 v176, 16, v156
	v_and_b32_e32 v174, 0xffff0000, v155
	v_mov_b32_e32 v175, v172
	v_pk_mov_b32 v[196:197], v[176:177], v[172:173] op_sel:[1,0]
	v_and_b32_e32 v166, 0xffff0000, v156
	v_lshlrev_b32_e32 v168, 16, v157
	v_lshlrev_b32_e32 v154, 16, v154
	v_and_b32_e32 v156, 0xffff0000, v157
	v_mov_b32_e32 v157, v174
	v_mov_b32_e32 v167, v177
	v_mov_b32_e32 v155, v174
	v_mov_b32_e32 v169, v174
	v_pk_add_f32 v[198:199], v[174:175], v[196:197]
	v_pk_mul_f32 v[174:175], v[174:175], v[196:197]
	v_pk_add_f32 v[172:173], v[154:155], v[172:173] op_sel_hi:[0,1]
	v_mov_b32_e32 v199, v175
	v_pk_add_f32 v[174:175], v[176:177], v[166:167]
	v_pk_mul_f32 v[196:197], v[176:177], v[176:177]
	v_mov_b32_e32 v167, v156
	v_mul_f32_e32 v173, v154, v154
	v_mov_b32_e32 v175, v197
	v_pk_add_f32 v[196:197], v[156:157], v[168:169]
	v_pk_mul_f32 v[154:155], v[156:157], v[154:155]
	v_mov_b32_e32 v177, v168
	v_pk_mul_f32 v[156:157], v[166:167], v[166:167]
	v_mov_b32_e32 v197, v155
	v_pk_fma_f32 v[156:157], v[176:177], v[176:177], v[156:157]
	v_pk_add_f32 v[172:173], v[172:173], v[198:199]
	v_pk_add_f32 v[154:155], v[174:175], v[196:197]
	v_pk_add_f32 v[156:157], v[156:157], v[156:157] op_sel_hi:[0,1]
	v_pk_add_f32 v[154:155], v[172:173], v[154:155]
	v_mov_b32_e32 v156, v1
	v_pk_fma_f32 v[152:153], v[164:165], s[72:73], v[152:153] op_sel_hi:[1,0,1]
	v_pk_fma_f32 v[150:151], v[162:163], s[72:73], v[150:151] op_sel_hi:[1,0,1]
	v_pk_fma_f32 v[148:149], v[160:161], s[72:73], v[148:149] op_sel_hi:[1,0,1]
	v_pk_fma_f32 v[146:147], v[158:159], s[72:73], v[146:147] op_sel_hi:[1,0,1]
	v_pk_add_f32 v[154:155], v[154:155], v[156:157]
	v_cvt_pk_bf16_f32 v150, v150, v151
	v_cvt_pk_bf16_f32 v151, v152, v153
	v_cvt_pk_bf16_f32 v152, v146, v147
	v_cvt_pk_bf16_f32 v153, v148, v149
	s_lshl_b32 s36, s36, 2
	v_lshlrev_b32_e32 v146, 16, v150
	v_and_b32_e32 v148, 0xffff0000, v150
	v_lshlrev_b32_e32 v156, 16, v151
	v_and_b32_e32 v158, 0xffff0000, v151
	v_lshlrev_b32_e32 v160, 16, v152
	v_and_b32_e32 v162, 0xffff0000, v152
	v_lshlrev_b32_e32 v164, 16, v153
	v_and_b32_e32 v166, 0xffff0000, v153
	v_mul_f32_e32 v147, v146, v146
	v_mul_f32_e32 v149, v148, v148
	v_mul_f32_e32 v157, v156, v156
	v_mul_f32_e32 v159, v158, v158
	v_mul_f32_e32 v161, v160, v160
	v_mul_f32_e32 v163, v162, v162
	v_mul_f32_e32 v165, v164, v164
	v_mul_f32_e32 v167, v166, v166
	v_pk_add_f32 v[146:147], v[146:147], v[148:149]
	v_pk_add_f32 v[148:149], v[156:157], v[158:159]
	v_pk_add_f32 v[156:157], v[164:165], v[166:167]
	v_pk_add_f32 v[146:147], v[146:147], v[148:149]
	v_pk_add_f32 v[148:149], v[160:161], v[162:163]
	s_ashr_i32 s37, s36, 31
	v_pk_add_f32 v[148:149], v[148:149], v[156:157]
	s_or_b64 s[36:37], s[36:37], s[2:3]
	v_pk_add_f32 v[146:147], v[146:147], v[148:149]
	flat_store_dwordx4 v[194:195], v[150:153] offset:16
	v_pk_add_f32 v[146:147], v[154:155], v[146:147]
	ds_bpermute_b32 v148, v213, v146
	ds_bpermute_b32 v149, v213, v147
	s_waitcnt lgkmcnt(0)
	v_pk_add_f32 v[146:147], v[146:147], v[148:149]
	ds_bpermute_b32 v148, v214, v146
	ds_bpermute_b32 v149, v214, v147
	s_and_saveexec_b64 s[38:39], s[0:1]
	s_cbranch_execz .LBB0_331
	v_lshlrev_b64 v[150:151], 8, v[192:193]
	v_lshl_add_u64 v[150:151], s[10:11], 0, v[150:151]
	v_lshl_add_u64 v[150:151], s[36:37], 3, v[150:151]
	s_waitcnt lgkmcnt(0)
	v_pk_add_f32 v[146:147], v[146:147], v[148:149]
	flat_store_dwordx2 v[150:151], v[146:147]

; __device__ __forceinline__ float bf_lo(unsigned w) { return __uint_as_float(w << 16); }
; __device__ __forceinline__ float bf_hi(unsigned w) { return __uint_as_float(w & 0xffff0000u); }
; __device__ __forceinline__ float shflx(float v, int k, int lane) { return __int_as_float(__builtin_amdgcn_ds_bpermute((lane ^ k) << 2, __float_as_int(v))); }
; __device__ __forceinline__ u32x4 pack8(const f32x4 a, const f32x4 b) { u32x4 w; w.x = cvt_pk_bf16(a[0], a[1]); w.y = cvt_pk_bf16(a[2], a[3]); w.z = cvt_pk_bf16(b[0], b[1]); w.w = cvt_pk_bf16(b[2], b[3]); return w; }
;     __device__ __forceinline__ void operator()(const f32x4 (&acc)[2][2][4][2], const pg8::Unit& u, int wr, int wc, int fr, int fq, LAS unsigned char* lds, int par) const {
;     ...
;                 for (int bj = 0; bj < 2; ++bj) {
;                     f32x4 r0, r1;
;                     if (prev) {
;                         const u32x4 w = *(const u32x4*)(tb + ro + bj * 8);
;                         r0 = (f32x4){bf_lo(w.x), bf_hi(w.x), bf_lo(w.y), bf_hi(w.y)}; r1 = (f32x4){bf_lo(w.z), bf_hi(w.z), bf_lo(w.w), bf_hi(w.w)};
;                         r0 = (r0 - mu) * rstd * gg[2 * bj] + bb[2 * bj]; r1 = (r1 - mu) * rstd * gg[2 * bj + 1] + bb[2 * bj + 1];
;                     } else { r0 = *(const f32x4*)(xin + ro + bj * 8); r1 = *(const f32x4*)(xin + ro + bj * 8 + 4); }
;                     const f32x4 t0 = r0 * ALPHA + acc[ai][bj][m][0], t1 = r1 * ALPHA + acc[ai][bj][m][1];
;                     if (xout != nullptr) { *(f32x4*)(xout + ro + bj * 8) = t0; *(f32x4*)(xout + ro + bj * 8 + 4) = t1; }
;                     const u32x4 pw = pack8(t0, t1);
;                     *(u32x4*)(tb + ro + bj * 8) = pw;
;                     const float a0 = bf_lo(pw.x), a1 = bf_hi(pw.x), a2 = bf_lo(pw.y), a3 = bf_hi(pw.y), a4 = bf_lo(pw.z), a5 = bf_hi(pw.z), a6 = bf_lo(pw.w), a7 = bf_hi(pw.w);
;                     s1 += ((a0 + a1) + (a2 + a3)) + ((a4 + a5) + (a6 + a7));
;                     s2 += ((a0 * a0 + a1 * a1) + (a2 * a2 + a3 * a3)) + ((a4 * a4 + a5 * a5) + (a6 * a6 + a7 * a7));
;                 }
;                 s1 += shflx(s1, 16, fr + 16 * fq); s1 += shflx(s1, 32, fr + 16 * fq); s2 += shflx(s2, 16, fr + 16 * fq); s2 += shflx(s2, 32, fr + 16 * fq);
;                 if (fq == 0) { float* sp = stats_out + ((size_t)row * 32 + u.pn * 4 + wc) * 2; sp[0] = s1; sp[1] = s2; }
.LBB0_336:
	s_andn2_b64 vcc, exec, s[38:39]
	v_lshl_add_u64 v[162:163], v[162:163], 2, s[12:13]
	s_cbranch_vccnz .LBB0_338
	s_waitcnt lgkmcnt(0)
	s_waitcnt vmcnt(3)
	v_mov_b32_e32 v146, v222
	v_mov_b32_e32 v147, v223
	v_mov_b32_e32 v148, v224
	v_mov_b32_e32 v149, v225
	v_mov_b32_e32 v150, v226
	v_mov_b32_e32 v151, v227
	v_mov_b32_e32 v152, v228
	v_mov_b32_e32 v153, v229
.LBB0_338:
	v_pk_fma_f32 v[144:145], v[152:153], s[72:73], v[144:145] op_sel_hi:[1,0,1]
	v_pk_fma_f32 v[142:143], v[150:151], s[72:73], v[142:143] op_sel_hi:[1,0,1]
	s_waitcnt lgkmcnt(0)
	v_pk_fma_f32 v[148:149], v[148:149], s[72:73], v[140:141] op_sel_hi:[1,0,1]
	v_pk_fma_f32 v[140:141], v[146:147], s[72:73], v[138:139] op_sel_hi:[1,0,1]
	s_and_b64 vcc, exec, s[6:7]
	s_mov_b64 s[38:39], -1
	v_cvt_pk_bf16_f32 v138, v142, v143
	v_cvt_pk_bf16_f32 v139, v144, v145
	v_cvt_pk_bf16_f32 v140, v140, v141
	v_cvt_pk_bf16_f32 v141, v148, v149
	flat_store_dwordx4 v[156:157], v[138:141]
	s_cbranch_vccnz .LBB0_340
	flat_load_dwordx4 v[142:145], v[156:157] offset:16
	v_mov_b32_e32 v146, v158
	v_mov_b32_e32 v147, v158
	s_mov_b64 s[38:39], 0
	s_waitcnt vmcnt(0) lgkmcnt(0)
	v_lshlrev_b32_e32 v148, 16, v142
	v_and_b32_e32 v149, 0xffff0000, v142
	v_lshlrev_b32_e32 v142, 16, v143
	v_and_b32_e32 v143, 0xffff0000, v143
	v_lshlrev_b32_e32 v150, 16, v144
	v_and_b32_e32 v151, 0xffff0000, v144
	v_lshlrev_b32_e32 v152, 16, v145
	v_and_b32_e32 v153, 0xffff0000, v145
	v_sub_f32_e32 v143, v143, v160
	v_sub_f32_e32 v142, v142, v160
	v_sub_f32_e32 v145, v149, v160
	v_sub_f32_e32 v144, v148, v160
	v_sub_f32_e32 v149, v153, v160
	v_sub_f32_e32 v148, v152, v160
	v_sub_f32_e32 v151, v151, v160
	v_sub_f32_e32 v150, v150, v160
	v_pk_mul_f32 v[144:145], v[158:159], v[144:145]
	v_pk_mul_f32 v[142:143], v[146:147], v[142:143]
	v_pk_mul_f32 v[150:151], v[158:159], v[150:151]
	v_pk_mul_f32 v[152:153], v[146:147], v[148:149]
	v_pk_fma_f32 v[148:149], v[44:45], v[142:143], v[48:49]
	v_pk_fma_f32 v[146:147], v[42:43], v[144:145], v[46:47]
	v_pk_fma_f32 v[144:145], v[36:37], v[152:153], v[40:41]
	v_pk_fma_f32 v[142:143], v[34:35], v[150:151], v[38:39]
.LBB0_340:
	s_andn2_b64 vcc, exec, s[38:39]
	s_cbranch_vccnz .LBB0_342
	s_waitcnt vmcnt(2)
	v_mov_b32_e32 v142, v230
	v_mov_b32_e32 v143, v231
	v_mov_b32_e32 v144, v232
	v_mov_b32_e32 v145, v233
	v_mov_b32_e32 v146, v234
	v_mov_b32_e32 v147, v235
	v_mov_b32_e32 v148, v236
	v_mov_b32_e32 v149, v237
	v_add_u32_e32 v238, 0x20000, v238
	global_load_dwordx4 v[222:225], v238, s[12:13] offset:16
	global_load_dwordx4 v[226:229], v238, s[12:13]
	global_load_dwordx4 v[230:233], v238, s[12:13] offset:48
	global_load_dwordx4 v[234:237], v238, s[12:13] offset:32
.LBB0_342:
	v_and_b32_e32 v159, 16, v138
	v_and_b32_e32 v158, 0xffff0000, v138
	v_lshlrev_b32_e32 v163, 16, v139
	v_lshlrev_b32_e32 v162, 16, v140
	v_and_b32_e32 v160, 0xffff0000, v139
	v_mov_b32_e32 v161, v158
	v_pk_mov_b32 v[164:165], v[162:163], v[158:159] op_sel:[1,0]
	v_and_b32_e32 v150, 0xffff0000, v140
	v_lshlrev_b32_e32 v152, 16, v141
	v_lshlrev_b32_e32 v138, 16, v138
	v_and_b32_e32 v140, 0xffff0000, v141
	v_mov_b32_e32 v141, v160
	v_mov_b32_e32 v151, v163
	v_mov_b32_e32 v139, v160
	v_mov_b32_e32 v153, v160
	v_pk_add_f32 v[166:167], v[160:161], v[164:165]
	v_pk_mul_f32 v[160:161], v[160:161], v[164:165]
	v_pk_add_f32 v[158:159], v[138:139], v[158:159] op_sel_hi:[0,1]
	v_mov_b32_e32 v167, v161
	v_pk_add_f32 v[160:161], v[162:163], v[150:151]
	v_pk_mul_f32 v[164:165], v[162:163], v[162:163]
	v_mov_b32_e32 v151, v140
	v_mul_f32_e32 v159, v138, v138
	v_mov_b32_e32 v161, v165
	v_pk_add_f32 v[164:165], v[140:141], v[152:153]
	v_pk_mul_f32 v[138:139], v[140:141], v[138:139]
	v_mov_b32_e32 v163, v152
	v_pk_mul_f32 v[140:141], v[150:151], v[150:151]
	v_mov_b32_e32 v165, v139
	v_pk_fma_f32 v[140:141], v[162:163], v[162:163], v[140:141]
	v_pk_add_f32 v[158:159], v[158:159], v[166:167]
	v_pk_add_f32 v[138:139], v[160:161], v[164:165]
	v_pk_add_f32 v[140:141], v[140:141], v[140:141] op_sel_hi:[0,1]
	v_pk_add_f32 v[138:139], v[158:159], v[138:139]
	v_mov_b32_e32 v140, v1
	v_pk_fma_f32 v[136:137], v[148:149], s[72:73], v[136:137] op_sel_hi:[1,0,1]
	v_pk_fma_f32 v[134:135], v[146:147], s[72:73], v[134:135] op_sel_hi:[1,0,1]
	v_pk_fma_f32 v[132:133], v[144:145], s[72:73], v[132:133] op_sel_hi:[1,0,1]
	v_pk_fma_f32 v[130:131], v[142:143], s[72:73], v[130:131] op_sel_hi:[1,0,1]
	v_pk_add_f32 v[138:139], v[138:139], v[140:141]
	v_cvt_pk_bf16_f32 v134, v134, v135
	v_cvt_pk_bf16_f32 v135, v136, v137
	v_cvt_pk_bf16_f32 v136, v130, v131
	v_cvt_pk_bf16_f32 v137, v132, v133
	flat_store_dwordx4 v[156:157], v[134:137] offset:16
	v_lshlrev_b32_e32 v130, 16, v134
	v_and_b32_e32 v132, 0xffff0000, v134
	v_lshlrev_b32_e32 v140, 16, v135
	v_and_b32_e32 v142, 0xffff0000, v135
	v_lshlrev_b32_e32 v144, 16, v136
	v_and_b32_e32 v146, 0xffff0000, v136
	v_lshlrev_b32_e32 v148, 16, v137
	v_and_b32_e32 v150, 0xffff0000, v137
	v_mul_f32_e32 v131, v130, v130
	v_mul_f32_e32 v133, v132, v132
	v_mul_f32_e32 v141, v140, v140
	v_mul_f32_e32 v143, v142, v142
	v_mul_f32_e32 v145, v144, v144
	v_mul_f32_e32 v147, v146, v146
	v_mul_f32_e32 v149, v148, v148
	v_mul_f32_e32 v151, v150, v150
	v_pk_add_f32 v[130:131], v[130:131], v[132:133]
	v_pk_add_f32 v[132:133], v[140:141], v[142:143]
	v_pk_add_f32 v[140:141], v[148:149], v[150:151]
	v_pk_add_f32 v[130:131], v[130:131], v[132:133]
	v_pk_add_f32 v[132:133], v[144:145], v[146:147]
	s_nop 0
	v_pk_add_f32 v[132:133], v[132:133], v[140:141]
	s_nop 0
	v_pk_add_f32 v[130:131], v[130:131], v[132:133]
	s_nop 0
	v_pk_add_f32 v[130:131], v[138:139], v[130:131]
	ds_bpermute_b32 v132, v213, v130
	ds_bpermute_b32 v133, v213, v131
	s_waitcnt lgkmcnt(0)
	v_pk_add_f32 v[130:131], v[130:131], v[132:133]
	ds_bpermute_b32 v132, v214, v130
	ds_bpermute_b32 v133, v214, v131
	s_and_saveexec_b64 s[38:39], s[0:1]
	s_cbranch_execz .LBB0_344
	v_lshlrev_b64 v[134:135], 8, v[154:155]
	v_lshl_add_u64 v[134:135], s[10:11], 0, v[134:135]
	v_lshl_add_u64 v[134:135], s[36:37], 3, v[134:135]
	s_waitcnt lgkmcnt(0)
	v_pk_add_f32 v[130:131], v[130:131], v[132:133]
	flat_store_dwordx2 v[134:135], v[130:131]

; __device__ __forceinline__ float bf_lo(unsigned w) { return __uint_as_float(w << 16); }
; __device__ __forceinline__ float bf_hi(unsigned w) { return __uint_as_float(w & 0xffff0000u); }
; __device__ __forceinline__ float shflx(float v, int k, int lane) { return __int_as_float(__builtin_amdgcn_ds_bpermute((lane ^ k) << 2, __float_as_int(v))); }
; __device__ __forceinline__ u32x4 pack8(const f32x4 a, const f32x4 b) { u32x4 w; w.x = cvt_pk_bf16(a[0], a[1]); w.y = cvt_pk_bf16(a[2], a[3]); w.z = cvt_pk_bf16(b[0], b[1]); w.w = cvt_pk_bf16(b[2], b[3]); return w; }
;     __device__ __forceinline__ void operator()(const f32x4 (&acc)[2][2][4][2], const pg8::Unit& u, int wr, int wc, int fr, int fq, LAS unsigned char* lds, int par) const {
;     ...
;                 for (int bj = 0; bj < 2; ++bj) {
;                     f32x4 r0, r1;
;                     if (prev) {
;                         const u32x4 w = *(const u32x4*)(tb + ro + bj * 8);
;                         r0 = (f32x4){bf_lo(w.x), bf_hi(w.x), bf_lo(w.y), bf_hi(w.y)}; r1 = (f32x4){bf_lo(w.z), bf_hi(w.z), bf_lo(w.w), bf_hi(w.w)};
;                         r0 = (r0 - mu) * rstd * gg[2 * bj] + bb[2 * bj]; r1 = (r1 - mu) * rstd * gg[2 * bj + 1] + bb[2 * bj + 1];
;                     } else { r0 = *(const f32x4*)(xin + ro + bj * 8); r1 = *(const f32x4*)(xin + ro + bj * 8 + 4); }
;                     const f32x4 t0 = r0 * ALPHA + acc[ai][bj][m][0], t1 = r1 * ALPHA + acc[ai][bj][m][1];
;                     if (xout != nullptr) { *(f32x4*)(xout + ro + bj * 8) = t0; *(f32x4*)(xout + ro + bj * 8 + 4) = t1; }
;                     const u32x4 pw = pack8(t0, t1);
;                     *(u32x4*)(tb + ro + bj * 8) = pw;
;                     const float a0 = bf_lo(pw.x), a1 = bf_hi(pw.x), a2 = bf_lo(pw.y), a3 = bf_hi(pw.y), a4 = bf_lo(pw.z), a5 = bf_hi(pw.z), a6 = bf_lo(pw.w), a7 = bf_hi(pw.w);
;                     s1 += ((a0 + a1) + (a2 + a3)) + ((a4 + a5) + (a6 + a7));
;                     s2 += ((a0 * a0 + a1 * a1) + (a2 * a2 + a3 * a3)) + ((a4 * a4 + a5 * a5) + (a6 * a6 + a7 * a7));
;                 }
;                 s1 += shflx(s1, 16, fr + 16 * fq); s1 += shflx(s1, 32, fr + 16 * fq); s2 += shflx(s2, 16, fr + 16 * fq); s2 += shflx(s2, 32, fr + 16 * fq);
;                 if (fq == 0) { float* sp = stats_out + ((size_t)row * 32 + u.pn * 4 + wc) * 2; sp[0] = s1; sp[1] = s2; }
.LBB0_349:
	s_andn2_b64 vcc, exec, s[38:39]
	v_lshl_add_u64 v[146:147], v[146:147], 2, s[12:13]
	s_cbranch_vccnz .LBB0_351
	s_waitcnt lgkmcnt(0)
	s_waitcnt vmcnt(3)
	v_mov_b32_e32 v130, v222
	v_mov_b32_e32 v131, v223
	v_mov_b32_e32 v132, v224
	v_mov_b32_e32 v133, v225
	v_mov_b32_e32 v134, v226
	v_mov_b32_e32 v135, v227
	v_mov_b32_e32 v136, v228
	v_mov_b32_e32 v137, v229
.LBB0_351:
	v_pk_fma_f32 v[128:129], v[136:137], s[72:73], v[128:129] op_sel_hi:[1,0,1]
	v_pk_fma_f32 v[126:127], v[134:135], s[72:73], v[126:127] op_sel_hi:[1,0,1]
	s_waitcnt lgkmcnt(0)
	v_pk_fma_f32 v[132:133], v[132:133], s[72:73], v[124:125] op_sel_hi:[1,0,1]
	v_pk_fma_f32 v[124:125], v[130:131], s[72:73], v[122:123] op_sel_hi:[1,0,1]
	s_and_b64 vcc, exec, s[6:7]
	s_mov_b64 s[38:39], -1
	v_cvt_pk_bf16_f32 v122, v126, v127
	v_cvt_pk_bf16_f32 v123, v128, v129
	v_cvt_pk_bf16_f32 v124, v124, v125
	v_cvt_pk_bf16_f32 v125, v132, v133
	flat_store_dwordx4 v[140:141], v[122:125]
	s_cbranch_vccnz .LBB0_353
	flat_load_dwordx4 v[126:129], v[140:141] offset:16
	v_mov_b32_e32 v130, v142
	v_mov_b32_e32 v131, v142
	s_mov_b64 s[38:39], 0
	s_waitcnt vmcnt(0) lgkmcnt(0)
	v_lshlrev_b32_e32 v132, 16, v126
	v_and_b32_e32 v133, 0xffff0000, v126
	v_lshlrev_b32_e32 v126, 16, v127
	v_and_b32_e32 v127, 0xffff0000, v127
	v_lshlrev_b32_e32 v134, 16, v128
	v_and_b32_e32 v135, 0xffff0000, v128
	v_lshlrev_b32_e32 v136, 16, v129
	v_and_b32_e32 v137, 0xffff0000, v129
	v_sub_f32_e32 v127, v127, v144
	v_sub_f32_e32 v126, v126, v144
	v_sub_f32_e32 v129, v133, v144
	v_sub_f32_e32 v128, v132, v144
	v_sub_f32_e32 v133, v137, v144
	v_sub_f32_e32 v132, v136, v144
	v_sub_f32_e32 v135, v135, v144
	v_sub_f32_e32 v134, v134, v144
	v_pk_mul_f32 v[128:129], v[142:143], v[128:129]
	v_pk_mul_f32 v[126:127], v[130:131], v[126:127]
	v_pk_mul_f32 v[134:135], v[142:143], v[134:135]
	v_pk_mul_f32 v[136:137], v[130:131], v[132:133]
	v_pk_fma_f32 v[132:133], v[44:45], v[126:127], v[48:49]
	v_pk_fma_f32 v[130:131], v[42:43], v[128:129], v[46:47]
	v_pk_fma_f32 v[128:129], v[36:37], v[136:137], v[40:41]
	v_pk_fma_f32 v[126:127], v[34:35], v[134:135], v[38:39]
.LBB0_353:
	s_andn2_b64 vcc, exec, s[38:39]
	s_cbranch_vccnz .LBB0_355
	s_waitcnt vmcnt(2)
	v_mov_b32_e32 v126, v230
	v_mov_b32_e32 v127, v231
	v_mov_b32_e32 v128, v232
	v_mov_b32_e32 v129, v233
	v_mov_b32_e32 v130, v234
	v_mov_b32_e32 v131, v235
	v_mov_b32_e32 v132, v236
	v_mov_b32_e32 v133, v237
	v_add_u32_e32 v238, 0x20000, v238
	global_load_dwordx4 v[222:225], v238, s[12:13] offset:16
	global_load_dwordx4 v[226:229], v238, s[12:13]
	global_load_dwordx4 v[230:233], v238, s[12:13] offset:48
	global_load_dwordx4 v[234:237], v238, s[12:13] offset:32
.LBB0_355:
	v_and_b32_e32 v143, 16, v122
	v_and_b32_e32 v142, 0xffff0000, v122
	v_lshlrev_b32_e32 v147, 16, v123
	v_lshlrev_b32_e32 v146, 16, v124
	v_and_b32_e32 v144, 0xffff0000, v123
	v_mov_b32_e32 v145, v142
	v_pk_mov_b32 v[148:149], v[146:147], v[142:143] op_sel:[1,0]
	v_and_b32_e32 v134, 0xffff0000, v124
	v_lshlrev_b32_e32 v136, 16, v125
	v_lshlrev_b32_e32 v122, 16, v122
	v_and_b32_e32 v124, 0xffff0000, v125
	v_mov_b32_e32 v125, v144
	v_mov_b32_e32 v135, v147
	v_mov_b32_e32 v123, v144
	v_mov_b32_e32 v137, v144
	v_pk_add_f32 v[150:151], v[144:145], v[148:149]
	v_pk_mul_f32 v[144:145], v[144:145], v[148:149]
	v_pk_add_f32 v[142:143], v[122:123], v[142:143] op_sel_hi:[0,1]
	v_mov_b32_e32 v151, v145
	v_pk_add_f32 v[144:145], v[146:147], v[134:135]
	v_pk_mul_f32 v[148:149], v[146:147], v[146:147]
	v_mov_b32_e32 v135, v124
	v_mul_f32_e32 v143, v122, v122
	v_mov_b32_e32 v145, v149
	v_pk_add_f32 v[148:149], v[124:125], v[136:137]
	v_pk_mul_f32 v[122:123], v[124:125], v[122:123]
	v_mov_b32_e32 v147, v136
	v_pk_mul_f32 v[124:125], v[134:135], v[134:135]
	v_mov_b32_e32 v149, v123
	v_pk_fma_f32 v[124:125], v[146:147], v[146:147], v[124:125]
	v_pk_add_f32 v[142:143], v[142:143], v[150:151]
	v_pk_add_f32 v[122:123], v[144:145], v[148:149]
	v_pk_add_f32 v[124:125], v[124:125], v[124:125] op_sel_hi:[0,1]
	v_pk_add_f32 v[122:123], v[142:143], v[122:123]
	v_mov_b32_e32 v124, v1
	v_pk_fma_f32 v[120:121], v[132:133], s[72:73], v[120:121] op_sel_hi:[1,0,1]
	v_pk_fma_f32 v[118:119], v[130:131], s[72:73], v[118:119] op_sel_hi:[1,0,1]
	v_pk_fma_f32 v[116:117], v[128:129], s[72:73], v[116:117] op_sel_hi:[1,0,1]
	v_pk_fma_f32 v[114:115], v[126:127], s[72:73], v[114:115] op_sel_hi:[1,0,1]
	v_pk_add_f32 v[122:123], v[122:123], v[124:125]
	v_cvt_pk_bf16_f32 v118, v118, v119
	v_cvt_pk_bf16_f32 v119, v120, v121
	v_cvt_pk_bf16_f32 v120, v114, v115
	v_cvt_pk_bf16_f32 v121, v116, v117
	flat_store_dwordx4 v[140:141], v[118:121] offset:16
	v_lshlrev_b32_e32 v114, 16, v118
	v_and_b32_e32 v116, 0xffff0000, v118
	v_lshlrev_b32_e32 v124, 16, v119
	v_and_b32_e32 v126, 0xffff0000, v119
	v_lshlrev_b32_e32 v128, 16, v120
	v_and_b32_e32 v130, 0xffff0000, v120
	v_lshlrev_b32_e32 v132, 16, v121
	v_and_b32_e32 v134, 0xffff0000, v121
	v_mul_f32_e32 v115, v114, v114
	v_mul_f32_e32 v117, v116, v116
	v_mul_f32_e32 v125, v124, v124
	v_mul_f32_e32 v127, v126, v126
	v_mul_f32_e32 v129, v128, v128
	v_mul_f32_e32 v131, v130, v130
	v_mul_f32_e32 v133, v132, v132
	v_mul_f32_e32 v135, v134, v134
	v_pk_add_f32 v[114:115], v[114:115], v[116:117]
	v_pk_add_f32 v[116:117], v[124:125], v[126:127]
	v_pk_add_f32 v[124:125], v[132:133], v[134:135]
	v_pk_add_f32 v[114:115], v[114:115], v[116:117]
	v_pk_add_f32 v[116:117], v[128:129], v[130:131]
	s_nop 0
	v_pk_add_f32 v[116:117], v[116:117], v[124:125]
	s_nop 0
	v_pk_add_f32 v[114:115], v[114:115], v[116:117]
	s_nop 0
	v_pk_add_f32 v[114:115], v[122:123], v[114:115]
	ds_bpermute_b32 v116, v213, v114
	ds_bpermute_b32 v117, v213, v115
	s_waitcnt lgkmcnt(0)
	v_pk_add_f32 v[114:115], v[114:115], v[116:117]
	ds_bpermute_b32 v116, v214, v114
	ds_bpermute_b32 v117, v214, v115
	s_and_saveexec_b64 s[38:39], s[0:1]
	s_cbranch_execz .LBB0_357
	v_lshlrev_b64 v[118:119], 8, v[138:139]
	v_lshl_add_u64 v[118:119], s[10:11], 0, v[118:119]
	v_lshl_add_u64 v[118:119], s[36:37], 3, v[118:119]
	s_waitcnt lgkmcnt(0)
	v_pk_add_f32 v[114:115], v[114:115], v[116:117]
	flat_store_dwordx2 v[118:119], v[114:115]

; __device__ __forceinline__ float bf_lo(unsigned w) { return __uint_as_float(w << 16); }
; __device__ __forceinline__ float bf_hi(unsigned w) { return __uint_as_float(w & 0xffff0000u); }
; __device__ __forceinline__ float shflx(float v, int k, int lane) { return __int_as_float(__builtin_amdgcn_ds_bpermute((lane ^ k) << 2, __float_as_int(v))); }
; __device__ __forceinline__ u32x4 pack8(const f32x4 a, const f32x4 b) { u32x4 w; w.x = cvt_pk_bf16(a[0], a[1]); w.y = cvt_pk_bf16(a[2], a[3]); w.z = cvt_pk_bf16(b[0], b[1]); w.w = cvt_pk_bf16(b[2], b[3]); return w; }
;     __device__ __forceinline__ void operator()(const f32x4 (&acc)[2][2][4][2], const pg8::Unit& u, int wr, int wc, int fr, int fq, LAS unsigned char* lds, int par) const {
;     ...
;                 for (int bj = 0; bj < 2; ++bj) {
;                     f32x4 r0, r1;
;                     if (prev) {
;                         const u32x4 w = *(const u32x4*)(tb + ro + bj * 8);
;                         r0 = (f32x4){bf_lo(w.x), bf_hi(w.x), bf_lo(w.y), bf_hi(w.y)}; r1 = (f32x4){bf_lo(w.z), bf_hi(w.z), bf_lo(w.w), bf_hi(w.w)};
;                         r0 = (r0 - mu) * rstd * gg[2 * bj] + bb[2 * bj]; r1 = (r1 - mu) * rstd * gg[2 * bj + 1] + bb[2 * bj + 1];
;                     } else { r0 = *(const f32x4*)(xin + ro + bj * 8); r1 = *(const f32x4*)(xin + ro + bj * 8 + 4); }
;                     const f32x4 t0 = r0 * ALPHA + acc[ai][bj][m][0], t1 = r1 * ALPHA + acc[ai][bj][m][1];
;                     if (xout != nullptr) { *(f32x4*)(xout + ro + bj * 8) = t0; *(f32x4*)(xout + ro + bj * 8 + 4) = t1; }
;                     const u32x4 pw = pack8(t0, t1);
;                     *(u32x4*)(tb + ro + bj * 8) = pw;
;                     const float a0 = bf_lo(pw.x), a1 = bf_hi(pw.x), a2 = bf_lo(pw.y), a3 = bf_hi(pw.y), a4 = bf_lo(pw.z), a5 = bf_hi(pw.z), a6 = bf_lo(pw.w), a7 = bf_hi(pw.w);
;                     s1 += ((a0 + a1) + (a2 + a3)) + ((a4 + a5) + (a6 + a7));
;                     s2 += ((a0 * a0 + a1 * a1) + (a2 * a2 + a3 * a3)) + ((a4 * a4 + a5 * a5) + (a6 * a6 + a7 * a7));
;                 }
;                 s1 += shflx(s1, 16, fr + 16 * fq); s1 += shflx(s1, 32, fr + 16 * fq); s2 += shflx(s2, 16, fr + 16 * fq); s2 += shflx(s2, 32, fr + 16 * fq);
;                 if (fq == 0) { float* sp = stats_out + ((size_t)row * 32 + u.pn * 4 + wc) * 2; sp[0] = s1; sp[1] = s2; }
.LBB0_362:
	s_andn2_b64 vcc, exec, s[38:39]
	v_lshl_add_u64 v[130:131], v[130:131], 2, s[12:13]
	s_cbranch_vccnz .LBB0_364
	s_waitcnt lgkmcnt(0)
	s_waitcnt vmcnt(3)
	v_mov_b32_e32 v114, v222
	v_mov_b32_e32 v115, v223
	v_mov_b32_e32 v116, v224
	v_mov_b32_e32 v117, v225
	v_mov_b32_e32 v118, v226
	v_mov_b32_e32 v119, v227
	v_mov_b32_e32 v120, v228
	v_mov_b32_e32 v121, v229
.LBB0_364:
	v_pk_fma_f32 v[112:113], v[120:121], s[72:73], v[112:113] op_sel_hi:[1,0,1]
	v_pk_fma_f32 v[110:111], v[118:119], s[72:73], v[110:111] op_sel_hi:[1,0,1]
	s_waitcnt lgkmcnt(0)
	v_pk_fma_f32 v[116:117], v[116:117], s[72:73], v[108:109] op_sel_hi:[1,0,1]
	v_pk_fma_f32 v[108:109], v[114:115], s[72:73], v[106:107] op_sel_hi:[1,0,1]
	s_and_b64 vcc, exec, s[6:7]
	s_mov_b64 s[38:39], -1
	v_cvt_pk_bf16_f32 v106, v110, v111
	v_cvt_pk_bf16_f32 v107, v112, v113
	v_cvt_pk_bf16_f32 v108, v108, v109
	v_cvt_pk_bf16_f32 v109, v116, v117
	flat_store_dwordx4 v[124:125], v[106:109]
	s_cbranch_vccnz .LBB0_366
	flat_load_dwordx4 v[110:113], v[124:125] offset:16
	v_mov_b32_e32 v114, v126
	v_mov_b32_e32 v115, v126
	s_mov_b64 s[38:39], 0
	s_waitcnt vmcnt(0) lgkmcnt(0)
	v_lshlrev_b32_e32 v116, 16, v110
	v_and_b32_e32 v117, 0xffff0000, v110
	v_lshlrev_b32_e32 v110, 16, v111
	v_and_b32_e32 v111, 0xffff0000, v111
	v_lshlrev_b32_e32 v118, 16, v112
	v_and_b32_e32 v119, 0xffff0000, v112
	v_lshlrev_b32_e32 v120, 16, v113
	v_and_b32_e32 v121, 0xffff0000, v113
	v_sub_f32_e32 v111, v111, v128
	v_sub_f32_e32 v110, v110, v128
	v_sub_f32_e32 v113, v117, v128
	v_sub_f32_e32 v112, v116, v128
	v_sub_f32_e32 v117, v121, v128
	v_sub_f32_e32 v116, v120, v128
	v_sub_f32_e32 v119, v119, v128
	v_sub_f32_e32 v118, v118, v128
	v_pk_mul_f32 v[112:113], v[126:127], v[112:113]
	v_pk_mul_f32 v[110:111], v[114:115], v[110:111]
	v_pk_mul_f32 v[118:119], v[126:127], v[118:119]
	v_pk_mul_f32 v[120:121], v[114:115], v[116:117]
	v_pk_fma_f32 v[116:117], v[44:45], v[110:111], v[48:49]
	v_pk_fma_f32 v[114:115], v[42:43], v[112:113], v[46:47]
	v_pk_fma_f32 v[112:113], v[36:37], v[120:121], v[40:41]
	v_pk_fma_f32 v[110:111], v[34:35], v[118:119], v[38:39]
.LBB0_366:
	s_andn2_b64 vcc, exec, s[38:39]
	s_cbranch_vccnz .LBB0_368
	s_waitcnt vmcnt(2)
	v_mov_b32_e32 v110, v230
	v_mov_b32_e32 v111, v231
	v_mov_b32_e32 v112, v232
	v_mov_b32_e32 v113, v233
	v_mov_b32_e32 v114, v234
	v_mov_b32_e32 v115, v235
	v_mov_b32_e32 v116, v236
	v_mov_b32_e32 v117, v237
	v_add_u32_e32 v238, 0xa0000, v238
	global_load_dwordx4 v[222:225], v238, s[12:13] offset:16
	global_load_dwordx4 v[226:229], v238, s[12:13]
	global_load_dwordx4 v[230:233], v238, s[12:13] offset:48
	global_load_dwordx4 v[234:237], v238, s[12:13] offset:32
.LBB0_368:
	v_and_b32_e32 v127, 16, v106
	v_and_b32_e32 v126, 0xffff0000, v106
	v_lshlrev_b32_e32 v131, 16, v107
	v_lshlrev_b32_e32 v130, 16, v108
	v_and_b32_e32 v128, 0xffff0000, v107
	v_mov_b32_e32 v129, v126
	v_pk_mov_b32 v[132:133], v[130:131], v[126:127] op_sel:[1,0]
	v_and_b32_e32 v118, 0xffff0000, v108
	v_lshlrev_b32_e32 v120, 16, v109
	v_lshlrev_b32_e32 v106, 16, v106
	v_and_b32_e32 v108, 0xffff0000, v109
	v_mov_b32_e32 v109, v128
	v_mov_b32_e32 v119, v131
	v_mov_b32_e32 v107, v128
	v_mov_b32_e32 v121, v128
	v_pk_add_f32 v[134:135], v[128:129], v[132:133]
	v_pk_mul_f32 v[128:129], v[128:129], v[132:133]
	v_pk_add_f32 v[126:127], v[106:107], v[126:127] op_sel_hi:[0,1]
	v_mov_b32_e32 v135, v129
	v_pk_add_f32 v[128:129], v[130:131], v[118:119]
	v_pk_mul_f32 v[132:133], v[130:131], v[130:131]
	v_mov_b32_e32 v119, v108
	v_mul_f32_e32 v127, v106, v106
	v_mov_b32_e32 v129, v133
	v_pk_add_f32 v[132:133], v[108:109], v[120:121]
	v_pk_mul_f32 v[106:107], v[108:109], v[106:107]
	v_mov_b32_e32 v131, v120
	v_pk_mul_f32 v[108:109], v[118:119], v[118:119]
	v_mov_b32_e32 v133, v107
	v_pk_fma_f32 v[108:109], v[130:131], v[130:131], v[108:109]
	v_pk_add_f32 v[126:127], v[126:127], v[134:135]
	v_pk_add_f32 v[106:107], v[128:129], v[132:133]
	v_pk_add_f32 v[108:109], v[108:109], v[108:109] op_sel_hi:[0,1]
	v_pk_add_f32 v[106:107], v[126:127], v[106:107]
	v_mov_b32_e32 v108, v1
	v_pk_fma_f32 v[104:105], v[116:117], s[72:73], v[104:105] op_sel_hi:[1,0,1]
	v_pk_fma_f32 v[102:103], v[114:115], s[72:73], v[102:103] op_sel_hi:[1,0,1]
	v_pk_fma_f32 v[100:101], v[112:113], s[72:73], v[100:101] op_sel_hi:[1,0,1]
	v_pk_fma_f32 v[98:99], v[110:111], s[72:73], v[98:99] op_sel_hi:[1,0,1]
	v_pk_add_f32 v[106:107], v[106:107], v[108:109]
	v_cvt_pk_bf16_f32 v102, v102, v103
	v_cvt_pk_bf16_f32 v103, v104, v105
	v_cvt_pk_bf16_f32 v104, v98, v99
	v_cvt_pk_bf16_f32 v105, v100, v101
	flat_store_dwordx4 v[124:125], v[102:105] offset:16
	v_lshlrev_b32_e32 v98, 16, v102
	v_and_b32_e32 v100, 0xffff0000, v102
	v_lshlrev_b32_e32 v108, 16, v103
	v_and_b32_e32 v110, 0xffff0000, v103
	v_lshlrev_b32_e32 v112, 16, v104
	v_and_b32_e32 v114, 0xffff0000, v104
	v_lshlrev_b32_e32 v116, 16, v105
	v_and_b32_e32 v118, 0xffff0000, v105
	v_mul_f32_e32 v99, v98, v98
	v_mul_f32_e32 v101, v100, v100
	v_mul_f32_e32 v109, v108, v108
	v_mul_f32_e32 v111, v110, v110
	v_mul_f32_e32 v113, v112, v112
	v_mul_f32_e32 v115, v114, v114
	v_mul_f32_e32 v117, v116, v116
	v_mul_f32_e32 v119, v118, v118
	v_pk_add_f32 v[98:99], v[98:99], v[100:101]
	v_pk_add_f32 v[100:101], v[108:109], v[110:111]
	v_pk_add_f32 v[108:109], v[116:117], v[118:119]
	v_pk_add_f32 v[98:99], v[98:99], v[100:101]
	v_pk_add_f32 v[100:101], v[112:113], v[114:115]
	s_nop 0
	v_pk_add_f32 v[100:101], v[100:101], v[108:109]
	s_nop 0
	v_pk_add_f32 v[98:99], v[98:99], v[100:101]
	s_nop 0
	v_pk_add_f32 v[98:99], v[106:107], v[98:99]
	ds_bpermute_b32 v100, v213, v98
	ds_bpermute_b32 v101, v213, v99
	s_waitcnt lgkmcnt(0)
	v_pk_add_f32 v[98:99], v[98:99], v[100:101]
	ds_bpermute_b32 v100, v214, v98
	ds_bpermute_b32 v101, v214, v99
	s_and_saveexec_b64 s[38:39], s[0:1]
	s_cbranch_execz .LBB0_370
	v_lshlrev_b64 v[102:103], 8, v[122:123]
	v_lshl_add_u64 v[102:103], s[10:11], 0, v[102:103]
	v_lshl_add_u64 v[102:103], s[36:37], 3, v[102:103]
	s_waitcnt lgkmcnt(0)
	v_pk_add_f32 v[98:99], v[98:99], v[100:101]
	flat_store_dwordx2 v[102:103], v[98:99]

; __device__ __forceinline__ float bf_lo(unsigned w) { return __uint_as_float(w << 16); }
; __device__ __forceinline__ float bf_hi(unsigned w) { return __uint_as_float(w & 0xffff0000u); }
; __device__ __forceinline__ float shflx(float v, int k, int lane) { return __int_as_float(__builtin_amdgcn_ds_bpermute((lane ^ k) << 2, __float_as_int(v))); }
; __device__ __forceinline__ u32x4 pack8(const f32x4 a, const f32x4 b) { u32x4 w; w.x = cvt_pk_bf16(a[0], a[1]); w.y = cvt_pk_bf16(a[2], a[3]); w.z = cvt_pk_bf16(b[0], b[1]); w.w = cvt_pk_bf16(b[2], b[3]); return w; }
;     __device__ __forceinline__ void operator()(const f32x4 (&acc)[2][2][4][2], const pg8::Unit& u, int wr, int wc, int fr, int fq, LAS unsigned char* lds, int par) const {
;     ...
;                 for (int bj = 0; bj < 2; ++bj) {
;                     f32x4 r0, r1;
;                     if (prev) {
;                         const u32x4 w = *(const u32x4*)(tb + ro + bj * 8);
;                         r0 = (f32x4){bf_lo(w.x), bf_hi(w.x), bf_lo(w.y), bf_hi(w.y)}; r1 = (f32x4){bf_lo(w.z), bf_hi(w.z), bf_lo(w.w), bf_hi(w.w)};
;                         r0 = (r0 - mu) * rstd * gg[2 * bj] + bb[2 * bj]; r1 = (r1 - mu) * rstd * gg[2 * bj + 1] + bb[2 * bj + 1];
;                     } else { r0 = *(const f32x4*)(xin + ro + bj * 8); r1 = *(const f32x4*)(xin + ro + bj * 8 + 4); }
;                     const f32x4 t0 = r0 * ALPHA + acc[ai][bj][m][0], t1 = r1 * ALPHA + acc[ai][bj][m][1];
;                     if (xout != nullptr) { *(f32x4*)(xout + ro + bj * 8) = t0; *(f32x4*)(xout + ro + bj * 8 + 4) = t1; }
;                     const u32x4 pw = pack8(t0, t1);
;                     *(u32x4*)(tb + ro + bj * 8) = pw;
;                     const float a0 = bf_lo(pw.x), a1 = bf_hi(pw.x), a2 = bf_lo(pw.y), a3 = bf_hi(pw.y), a4 = bf_lo(pw.z), a5 = bf_hi(pw.z), a6 = bf_lo(pw.w), a7 = bf_hi(pw.w);
;                     s1 += ((a0 + a1) + (a2 + a3)) + ((a4 + a5) + (a6 + a7));
;                     s2 += ((a0 * a0 + a1 * a1) + (a2 * a2 + a3 * a3)) + ((a4 * a4 + a5 * a5) + (a6 * a6 + a7 * a7));
;                 }
;                 s1 += shflx(s1, 16, fr + 16 * fq); s1 += shflx(s1, 32, fr + 16 * fq); s2 += shflx(s2, 16, fr + 16 * fq); s2 += shflx(s2, 32, fr + 16 * fq);
;                 if (fq == 0) { float* sp = stats_out + ((size_t)row * 32 + u.pn * 4 + wc) * 2; sp[0] = s1; sp[1] = s2; }
.LBB0_375:
	s_andn2_b64 vcc, exec, s[38:39]
	v_lshl_add_u64 v[114:115], v[114:115], 2, s[12:13]
	s_cbranch_vccnz .LBB0_377
	s_waitcnt lgkmcnt(0)
	s_waitcnt vmcnt(3)
	v_mov_b32_e32 v98, v222
	v_mov_b32_e32 v99, v223
	v_mov_b32_e32 v100, v224
	v_mov_b32_e32 v101, v225
	v_mov_b32_e32 v102, v226
	v_mov_b32_e32 v103, v227
	v_mov_b32_e32 v104, v228
	v_mov_b32_e32 v105, v229
.LBB0_377:
	v_pk_fma_f32 v[96:97], v[104:105], s[72:73], v[96:97] op_sel_hi:[1,0,1]
	v_pk_fma_f32 v[94:95], v[102:103], s[72:73], v[94:95] op_sel_hi:[1,0,1]
	s_waitcnt lgkmcnt(0)
	v_pk_fma_f32 v[100:101], v[100:101], s[72:73], v[92:93] op_sel_hi:[1,0,1]
	v_pk_fma_f32 v[92:93], v[98:99], s[72:73], v[90:91] op_sel_hi:[1,0,1]
	s_and_b64 vcc, exec, s[6:7]
	s_mov_b64 s[38:39], -1
	v_cvt_pk_bf16_f32 v90, v94, v95
	v_cvt_pk_bf16_f32 v91, v96, v97
	v_cvt_pk_bf16_f32 v92, v92, v93
	v_cvt_pk_bf16_f32 v93, v100, v101
	flat_store_dwordx4 v[108:109], v[90:93]
	s_cbranch_vccnz .LBB0_379
	flat_load_dwordx4 v[94:97], v[108:109] offset:16
	v_mov_b32_e32 v98, v110
	v_mov_b32_e32 v99, v110
	s_mov_b64 s[38:39], 0
	s_waitcnt vmcnt(0) lgkmcnt(0)
	v_lshlrev_b32_e32 v100, 16, v94
	v_and_b32_e32 v101, 0xffff0000, v94
	v_lshlrev_b32_e32 v94, 16, v95
	v_and_b32_e32 v95, 0xffff0000, v95
	v_lshlrev_b32_e32 v102, 16, v96
	v_and_b32_e32 v103, 0xffff0000, v96
	v_lshlrev_b32_e32 v104, 16, v97
	v_and_b32_e32 v105, 0xffff0000, v97
	v_sub_f32_e32 v95, v95, v112
	v_sub_f32_e32 v94, v94, v112
	v_sub_f32_e32 v97, v101, v112
	v_sub_f32_e32 v96, v100, v112
	v_sub_f32_e32 v101, v105, v112
	v_sub_f32_e32 v100, v104, v112
	v_sub_f32_e32 v103, v103, v112
	v_sub_f32_e32 v102, v102, v112
	v_pk_mul_f32 v[96:97], v[110:111], v[96:97]
	v_pk_mul_f32 v[94:95], v[98:99], v[94:95]
	v_pk_mul_f32 v[102:103], v[110:111], v[102:103]
	v_pk_mul_f32 v[104:105], v[98:99], v[100:101]
	v_pk_fma_f32 v[100:101], v[44:45], v[94:95], v[48:49]
	v_pk_fma_f32 v[98:99], v[42:43], v[96:97], v[46:47]
	v_pk_fma_f32 v[96:97], v[36:37], v[104:105], v[40:41]
	v_pk_fma_f32 v[94:95], v[34:35], v[102:103], v[38:39]
.LBB0_379:
	s_andn2_b64 vcc, exec, s[38:39]
	s_cbranch_vccnz .LBB0_381
	s_waitcnt vmcnt(2)
	v_mov_b32_e32 v94, v230
	v_mov_b32_e32 v95, v231
	v_mov_b32_e32 v96, v232
	v_mov_b32_e32 v97, v233
	v_mov_b32_e32 v98, v234
	v_mov_b32_e32 v99, v235
	v_mov_b32_e32 v100, v236
	v_mov_b32_e32 v101, v237
	v_add_u32_e32 v238, 0x20000, v238
	global_load_dwordx4 v[222:225], v238, s[12:13] offset:16
	global_load_dwordx4 v[226:229], v238, s[12:13]
	global_load_dwordx4 v[230:233], v238, s[12:13] offset:48
	global_load_dwordx4 v[234:237], v238, s[12:13] offset:32
.LBB0_381:
	v_and_b32_e32 v111, 16, v90
	v_and_b32_e32 v110, 0xffff0000, v90
	v_lshlrev_b32_e32 v115, 16, v91
	v_lshlrev_b32_e32 v114, 16, v92
	v_and_b32_e32 v112, 0xffff0000, v91
	v_mov_b32_e32 v113, v110
	v_pk_mov_b32 v[116:117], v[114:115], v[110:111] op_sel:[1,0]
	v_and_b32_e32 v102, 0xffff0000, v92
	v_lshlrev_b32_e32 v104, 16, v93
	v_lshlrev_b32_e32 v90, 16, v90
	v_and_b32_e32 v92, 0xffff0000, v93
	v_mov_b32_e32 v93, v112
	v_mov_b32_e32 v103, v115
	v_mov_b32_e32 v91, v112
	v_mov_b32_e32 v105, v112
	v_pk_add_f32 v[118:119], v[112:113], v[116:117]
	v_pk_mul_f32 v[112:113], v[112:113], v[116:117]
	v_pk_add_f32 v[110:111], v[90:91], v[110:111] op_sel_hi:[0,1]
	v_mov_b32_e32 v119, v113
	v_pk_add_f32 v[112:113], v[114:115], v[102:103]
	v_pk_mul_f32 v[116:117], v[114:115], v[114:115]
	v_mov_b32_e32 v103, v92
	v_mul_f32_e32 v111, v90, v90
	v_mov_b32_e32 v113, v117
	v_pk_add_f32 v[116:117], v[92:93], v[104:105]
	v_pk_mul_f32 v[90:91], v[92:93], v[90:91]
	v_mov_b32_e32 v115, v104
	v_pk_mul_f32 v[92:93], v[102:103], v[102:103]
	v_mov_b32_e32 v117, v91
	v_pk_fma_f32 v[92:93], v[114:115], v[114:115], v[92:93]
	v_pk_add_f32 v[110:111], v[110:111], v[118:119]
	v_pk_add_f32 v[90:91], v[112:113], v[116:117]
	v_pk_add_f32 v[92:93], v[92:93], v[92:93] op_sel_hi:[0,1]
	v_pk_add_f32 v[90:91], v[110:111], v[90:91]
	v_mov_b32_e32 v92, v1
	v_pk_fma_f32 v[88:89], v[100:101], s[72:73], v[88:89] op_sel_hi:[1,0,1]
	v_pk_fma_f32 v[86:87], v[98:99], s[72:73], v[86:87] op_sel_hi:[1,0,1]
	v_pk_fma_f32 v[84:85], v[96:97], s[72:73], v[84:85] op_sel_hi:[1,0,1]
	v_pk_fma_f32 v[82:83], v[94:95], s[72:73], v[82:83] op_sel_hi:[1,0,1]
	v_pk_add_f32 v[90:91], v[90:91], v[92:93]
	v_cvt_pk_bf16_f32 v86, v86, v87
	v_cvt_pk_bf16_f32 v87, v88, v89
	v_cvt_pk_bf16_f32 v88, v82, v83
	v_cvt_pk_bf16_f32 v89, v84, v85
	flat_store_dwordx4 v[108:109], v[86:89] offset:16
	v_lshlrev_b32_e32 v82, 16, v86
	v_and_b32_e32 v84, 0xffff0000, v86
	v_lshlrev_b32_e32 v92, 16, v87
	v_and_b32_e32 v94, 0xffff0000, v87
	v_lshlrev_b32_e32 v96, 16, v88
	v_and_b32_e32 v98, 0xffff0000, v88
	v_lshlrev_b32_e32 v100, 16, v89
	v_and_b32_e32 v102, 0xffff0000, v89
	v_mul_f32_e32 v83, v82, v82
	v_mul_f32_e32 v85, v84, v84
	v_mul_f32_e32 v93, v92, v92
	v_mul_f32_e32 v95, v94, v94
	v_mul_f32_e32 v97, v96, v96
	v_mul_f32_e32 v99, v98, v98
	v_mul_f32_e32 v101, v100, v100
	v_mul_f32_e32 v103, v102, v102
	v_pk_add_f32 v[82:83], v[82:83], v[84:85]
	v_pk_add_f32 v[84:85], v[92:93], v[94:95]
	v_pk_add_f32 v[92:93], v[100:101], v[102:103]
	v_pk_add_f32 v[82:83], v[82:83], v[84:85]
	v_pk_add_f32 v[84:85], v[96:97], v[98:99]
	s_nop 0
	v_pk_add_f32 v[84:85], v[84:85], v[92:93]
	s_nop 0
	v_pk_add_f32 v[82:83], v[82:83], v[84:85]
	s_nop 0
	v_pk_add_f32 v[82:83], v[90:91], v[82:83]
	ds_bpermute_b32 v84, v213, v82
	ds_bpermute_b32 v85, v213, v83
	s_waitcnt lgkmcnt(0)
	v_pk_add_f32 v[82:83], v[82:83], v[84:85]
	ds_bpermute_b32 v84, v214, v82
	ds_bpermute_b32 v85, v214, v83
	s_and_saveexec_b64 s[38:39], s[0:1]
	s_cbranch_execz .LBB0_383
	v_lshlrev_b64 v[86:87], 8, v[106:107]
	v_lshl_add_u64 v[86:87], s[10:11], 0, v[86:87]
	v_lshl_add_u64 v[86:87], s[36:37], 3, v[86:87]
	s_waitcnt lgkmcnt(0)
	v_pk_add_f32 v[82:83], v[82:83], v[84:85]
	flat_store_dwordx2 v[86:87], v[82:83]

; __device__ __forceinline__ float bf_lo(unsigned w) { return __uint_as_float(w << 16); }
; __device__ __forceinline__ float bf_hi(unsigned w) { return __uint_as_float(w & 0xffff0000u); }
; __device__ __forceinline__ float shflx(float v, int k, int lane) { return __int_as_float(__builtin_amdgcn_ds_bpermute((lane ^ k) << 2, __float_as_int(v))); }
; __device__ __forceinline__ u32x4 pack8(const f32x4 a, const f32x4 b) { u32x4 w; w.x = cvt_pk_bf16(a[0], a[1]); w.y = cvt_pk_bf16(a[2], a[3]); w.z = cvt_pk_bf16(b[0], b[1]); w.w = cvt_pk_bf16(b[2], b[3]); return w; }
;     __device__ __forceinline__ void operator()(const f32x4 (&acc)[2][2][4][2], const pg8::Unit& u, int wr, int wc, int fr, int fq, LAS unsigned char* lds, int par) const {
;     ...
;                 for (int bj = 0; bj < 2; ++bj) {
;                     f32x4 r0, r1;
;                     if (prev) {
;                         const u32x4 w = *(const u32x4*)(tb + ro + bj * 8);
;                         r0 = (f32x4){bf_lo(w.x), bf_hi(w.x), bf_lo(w.y), bf_hi(w.y)}; r1 = (f32x4){bf_lo(w.z), bf_hi(w.z), bf_lo(w.w), bf_hi(w.w)};
;                         r0 = (r0 - mu) * rstd * gg[2 * bj] + bb[2 * bj]; r1 = (r1 - mu) * rstd * gg[2 * bj + 1] + bb[2 * bj + 1];
;                     } else { r0 = *(const f32x4*)(xin + ro + bj * 8); r1 = *(const f32x4*)(xin + ro + bj * 8 + 4); }
;                     const f32x4 t0 = r0 * ALPHA + acc[ai][bj][m][0], t1 = r1 * ALPHA + acc[ai][bj][m][1];
;                     if (xout != nullptr) { *(f32x4*)(xout + ro + bj * 8) = t0; *(f32x4*)(xout + ro + bj * 8 + 4) = t1; }
;                     const u32x4 pw = pack8(t0, t1);
;                     *(u32x4*)(tb + ro + bj * 8) = pw;
;                     const float a0 = bf_lo(pw.x), a1 = bf_hi(pw.x), a2 = bf_lo(pw.y), a3 = bf_hi(pw.y), a4 = bf_lo(pw.z), a5 = bf_hi(pw.z), a6 = bf_lo(pw.w), a7 = bf_hi(pw.w);
;                     s1 += ((a0 + a1) + (a2 + a3)) + ((a4 + a5) + (a6 + a7));
;                     s2 += ((a0 * a0 + a1 * a1) + (a2 * a2 + a3 * a3)) + ((a4 * a4 + a5 * a5) + (a6 * a6 + a7 * a7));
;                 }
;                 s1 += shflx(s1, 16, fr + 16 * fq); s1 += shflx(s1, 32, fr + 16 * fq); s2 += shflx(s2, 16, fr + 16 * fq); s2 += shflx(s2, 32, fr + 16 * fq);
;                 if (fq == 0) { float* sp = stats_out + ((size_t)row * 32 + u.pn * 4 + wc) * 2; sp[0] = s1; sp[1] = s2; }
.LBB0_388:
	s_andn2_b64 vcc, exec, s[38:39]
	v_lshl_add_u64 v[98:99], v[98:99], 2, s[12:13]
	s_cbranch_vccnz .LBB0_390
	s_waitcnt lgkmcnt(0)
	s_waitcnt vmcnt(3)
	v_mov_b32_e32 v82, v222
	v_mov_b32_e32 v83, v223
	v_mov_b32_e32 v84, v224
	v_mov_b32_e32 v85, v225
	v_mov_b32_e32 v86, v226
	v_mov_b32_e32 v87, v227
	v_mov_b32_e32 v88, v228
	v_mov_b32_e32 v89, v229
.LBB0_390:
	v_pk_fma_f32 v[80:81], v[88:89], s[72:73], v[80:81] op_sel_hi:[1,0,1]
	v_pk_fma_f32 v[78:79], v[86:87], s[72:73], v[78:79] op_sel_hi:[1,0,1]
	s_waitcnt lgkmcnt(0)
	v_pk_fma_f32 v[84:85], v[84:85], s[72:73], v[76:77] op_sel_hi:[1,0,1]
	v_pk_fma_f32 v[76:77], v[82:83], s[72:73], v[74:75] op_sel_hi:[1,0,1]
	s_and_b64 vcc, exec, s[6:7]
	s_mov_b64 s[38:39], -1
	v_cvt_pk_bf16_f32 v74, v78, v79
	v_cvt_pk_bf16_f32 v75, v80, v81
	v_cvt_pk_bf16_f32 v76, v76, v77
	v_cvt_pk_bf16_f32 v77, v84, v85
	flat_store_dwordx4 v[92:93], v[74:77]
	s_cbranch_vccnz .LBB0_392
	flat_load_dwordx4 v[78:81], v[92:93] offset:16
	v_mov_b32_e32 v82, v94
	v_mov_b32_e32 v83, v94
	s_mov_b64 s[38:39], 0
	s_waitcnt vmcnt(0) lgkmcnt(0)
	v_lshlrev_b32_e32 v84, 16, v78
	v_and_b32_e32 v85, 0xffff0000, v78
	v_lshlrev_b32_e32 v78, 16, v79
	v_and_b32_e32 v79, 0xffff0000, v79
	v_lshlrev_b32_e32 v86, 16, v80
	v_and_b32_e32 v87, 0xffff0000, v80
	v_lshlrev_b32_e32 v88, 16, v81
	v_and_b32_e32 v89, 0xffff0000, v81
	v_sub_f32_e32 v79, v79, v96
	v_sub_f32_e32 v78, v78, v96
	v_sub_f32_e32 v81, v85, v96
	v_sub_f32_e32 v80, v84, v96
	v_sub_f32_e32 v85, v89, v96
	v_sub_f32_e32 v84, v88, v96
	v_sub_f32_e32 v87, v87, v96
	v_sub_f32_e32 v86, v86, v96
	v_pk_mul_f32 v[80:81], v[94:95], v[80:81]
	v_pk_mul_f32 v[78:79], v[82:83], v[78:79]
	v_pk_mul_f32 v[86:87], v[94:95], v[86:87]
	v_pk_mul_f32 v[88:89], v[82:83], v[84:85]
	v_pk_fma_f32 v[84:85], v[44:45], v[78:79], v[48:49]
	v_pk_fma_f32 v[82:83], v[42:43], v[80:81], v[46:47]
	v_pk_fma_f32 v[80:81], v[36:37], v[88:89], v[40:41]
	v_pk_fma_f32 v[78:79], v[34:35], v[86:87], v[38:39]
.LBB0_392:
	s_andn2_b64 vcc, exec, s[38:39]
	s_cbranch_vccnz .LBB0_394
	s_waitcnt vmcnt(2)
	v_mov_b32_e32 v78, v230
	v_mov_b32_e32 v79, v231
	v_mov_b32_e32 v80, v232
	v_mov_b32_e32 v81, v233
	v_mov_b32_e32 v82, v234
	v_mov_b32_e32 v83, v235
	v_mov_b32_e32 v84, v236
	v_mov_b32_e32 v85, v237
	v_add_u32_e32 v238, 0x20000, v238
	global_load_dwordx4 v[222:225], v238, s[12:13] offset:16
	global_load_dwordx4 v[226:229], v238, s[12:13]
	global_load_dwordx4 v[230:233], v238, s[12:13] offset:48
	global_load_dwordx4 v[234:237], v238, s[12:13] offset:32
.LBB0_394:
	v_and_b32_e32 v95, 16, v74
	v_and_b32_e32 v94, 0xffff0000, v74
	v_lshlrev_b32_e32 v99, 16, v75
	v_lshlrev_b32_e32 v98, 16, v76
	v_and_b32_e32 v96, 0xffff0000, v75
	v_mov_b32_e32 v97, v94
	v_pk_mov_b32 v[100:101], v[98:99], v[94:95] op_sel:[1,0]
	v_and_b32_e32 v86, 0xffff0000, v76
	v_lshlrev_b32_e32 v88, 16, v77
	v_lshlrev_b32_e32 v74, 16, v74
	v_and_b32_e32 v76, 0xffff0000, v77
	v_mov_b32_e32 v77, v96
	v_mov_b32_e32 v87, v99
	v_mov_b32_e32 v75, v96
	v_mov_b32_e32 v89, v96
	v_pk_add_f32 v[102:103], v[96:97], v[100:101]
	v_pk_mul_f32 v[96:97], v[96:97], v[100:101]
	v_pk_add_f32 v[94:95], v[74:75], v[94:95] op_sel_hi:[0,1]
	v_mov_b32_e32 v103, v97
	v_pk_add_f32 v[96:97], v[98:99], v[86:87]
	v_pk_mul_f32 v[100:101], v[98:99], v[98:99]
	v_mov_b32_e32 v87, v76
	v_mul_f32_e32 v95, v74, v74
	v_mov_b32_e32 v97, v101
	v_pk_add_f32 v[100:101], v[76:77], v[88:89]
	v_pk_mul_f32 v[74:75], v[76:77], v[74:75]
	v_mov_b32_e32 v99, v88
	v_pk_mul_f32 v[76:77], v[86:87], v[86:87]
	v_mov_b32_e32 v101, v75
	v_pk_fma_f32 v[76:77], v[98:99], v[98:99], v[76:77]
	v_pk_add_f32 v[94:95], v[94:95], v[102:103]
	v_pk_add_f32 v[74:75], v[96:97], v[100:101]
	v_pk_add_f32 v[76:77], v[76:77], v[76:77] op_sel_hi:[0,1]
	v_pk_add_f32 v[74:75], v[94:95], v[74:75]
	v_mov_b32_e32 v76, v1
	v_pk_fma_f32 v[56:57], v[84:85], s[72:73], v[56:57] op_sel_hi:[1,0,1]
	v_pk_fma_f32 v[54:55], v[82:83], s[72:73], v[54:55] op_sel_hi:[1,0,1]
	v_pk_fma_f32 v[52:53], v[80:81], s[72:73], v[52:53] op_sel_hi:[1,0,1]
	v_pk_fma_f32 v[50:51], v[78:79], s[72:73], v[50:51] op_sel_hi:[1,0,1]
	v_pk_add_f32 v[74:75], v[74:75], v[76:77]
	v_cvt_pk_bf16_f32 v54, v54, v55
	v_cvt_pk_bf16_f32 v55, v56, v57
	v_cvt_pk_bf16_f32 v56, v50, v51
	v_cvt_pk_bf16_f32 v57, v52, v53
	flat_store_dwordx4 v[92:93], v[54:57] offset:16
	v_lshlrev_b32_e32 v50, 16, v54
	v_and_b32_e32 v52, 0xffff0000, v54
	v_lshlrev_b32_e32 v76, 16, v55
	v_and_b32_e32 v78, 0xffff0000, v55
	v_lshlrev_b32_e32 v80, 16, v56
	v_and_b32_e32 v82, 0xffff0000, v56
	v_lshlrev_b32_e32 v84, 16, v57
	v_and_b32_e32 v86, 0xffff0000, v57
	v_mul_f32_e32 v51, v50, v50
	v_mul_f32_e32 v53, v52, v52
	v_mul_f32_e32 v77, v76, v76
	v_mul_f32_e32 v79, v78, v78
	v_mul_f32_e32 v81, v80, v80
	v_mul_f32_e32 v83, v82, v82
	v_mul_f32_e32 v85, v84, v84
	v_mul_f32_e32 v87, v86, v86
	v_pk_add_f32 v[50:51], v[50:51], v[52:53]
	v_pk_add_f32 v[52:53], v[76:77], v[78:79]
	v_pk_add_f32 v[76:77], v[84:85], v[86:87]
	v_pk_add_f32 v[50:51], v[50:51], v[52:53]
	v_pk_add_f32 v[52:53], v[80:81], v[82:83]
	s_nop 0
	v_pk_add_f32 v[52:53], v[52:53], v[76:77]
	s_nop 0
	v_pk_add_f32 v[50:51], v[50:51], v[52:53]
	s_nop 0
	v_pk_add_f32 v[50:51], v[74:75], v[50:51]
	ds_bpermute_b32 v52, v213, v50
	ds_bpermute_b32 v53, v213, v51
	s_waitcnt lgkmcnt(0)
	v_pk_add_f32 v[50:51], v[50:51], v[52:53]
	ds_bpermute_b32 v52, v214, v50
	ds_bpermute_b32 v53, v214, v51
	s_and_saveexec_b64 s[38:39], s[0:1]
	s_cbranch_execz .LBB0_396
	v_lshlrev_b64 v[54:55], 8, v[90:91]
	v_lshl_add_u64 v[54:55], s[10:11], 0, v[54:55]
	v_lshl_add_u64 v[54:55], s[36:37], 3, v[54:55]
	s_waitcnt lgkmcnt(0)
	v_pk_add_f32 v[50:51], v[50:51], v[52:53]
	flat_store_dwordx2 v[54:55], v[50:51]

; __device__ __forceinline__ float bf_lo(unsigned w) { return __uint_as_float(w << 16); }
; __device__ __forceinline__ float bf_hi(unsigned w) { return __uint_as_float(w & 0xffff0000u); }
; __device__ __forceinline__ float shflx(float v, int k, int lane) { return __int_as_float(__builtin_amdgcn_ds_bpermute((lane ^ k) << 2, __float_as_int(v))); }
; __device__ __forceinline__ u32x4 pack8(const f32x4 a, const f32x4 b) { u32x4 w; w.x = cvt_pk_bf16(a[0], a[1]); w.y = cvt_pk_bf16(a[2], a[3]); w.z = cvt_pk_bf16(b[0], b[1]); w.w = cvt_pk_bf16(b[2], b[3]); return w; }
;     __device__ __forceinline__ void operator()(const f32x4 (&acc)[2][2][4][2], const pg8::Unit& u, int wr, int wc, int fr, int fq, LAS unsigned char* lds, int par) const {
;     ...
;                 for (int bj = 0; bj < 2; ++bj) {
;                     f32x4 r0, r1;
;                     if (prev) {
;                         const u32x4 w = *(const u32x4*)(tb + ro + bj * 8);
;                         r0 = (f32x4){bf_lo(w.x), bf_hi(w.x), bf_lo(w.y), bf_hi(w.y)}; r1 = (f32x4){bf_lo(w.z), bf_hi(w.z), bf_lo(w.w), bf_hi(w.w)};
;                         r0 = (r0 - mu) * rstd * gg[2 * bj] + bb[2 * bj]; r1 = (r1 - mu) * rstd * gg[2 * bj + 1] + bb[2 * bj + 1];
;                     } else { r0 = *(const f32x4*)(xin + ro + bj * 8); r1 = *(const f32x4*)(xin + ro + bj * 8 + 4); }
;                     const f32x4 t0 = r0 * ALPHA + acc[ai][bj][m][0], t1 = r1 * ALPHA + acc[ai][bj][m][1];
;                     if (xout != nullptr) { *(f32x4*)(xout + ro + bj * 8) = t0; *(f32x4*)(xout + ro + bj * 8 + 4) = t1; }
;                     const u32x4 pw = pack8(t0, t1);
;                     *(u32x4*)(tb + ro + bj * 8) = pw;
;                     const float a0 = bf_lo(pw.x), a1 = bf_hi(pw.x), a2 = bf_lo(pw.y), a3 = bf_hi(pw.y), a4 = bf_lo(pw.z), a5 = bf_hi(pw.z), a6 = bf_lo(pw.w), a7 = bf_hi(pw.w);
;                     s1 += ((a0 + a1) + (a2 + a3)) + ((a4 + a5) + (a6 + a7));
;                     s2 += ((a0 * a0 + a1 * a1) + (a2 * a2 + a3 * a3)) + ((a4 * a4 + a5 * a5) + (a6 * a6 + a7 * a7));
;                 }
;                 s1 += shflx(s1, 16, fr + 16 * fq); s1 += shflx(s1, 32, fr + 16 * fq); s2 += shflx(s2, 16, fr + 16 * fq); s2 += shflx(s2, 32, fr + 16 * fq);
;                 if (fq == 0) { float* sp = stats_out + ((size_t)row * 32 + u.pn * 4 + wc) * 2; sp[0] = s1; sp[1] = s2; }
.LBB0_401:
	s_andn2_b64 vcc, exec, s[38:39]
	v_lshl_add_u64 v[82:83], v[82:83], 2, s[12:13]
	s_cbranch_vccnz .LBB0_403
	s_waitcnt lgkmcnt(0)
	s_waitcnt vmcnt(3)
	v_mov_b32_e32 v50, v222
	v_mov_b32_e32 v51, v223
	v_mov_b32_e32 v52, v224
	v_mov_b32_e32 v53, v225
	v_mov_b32_e32 v54, v226
	v_mov_b32_e32 v55, v227
	v_mov_b32_e32 v56, v228
	v_mov_b32_e32 v57, v229
.LBB0_403:
	v_pk_fma_f32 v[32:33], v[56:57], s[72:73], v[32:33] op_sel_hi:[1,0,1]
	v_pk_fma_f32 v[30:31], v[54:55], s[72:73], v[30:31] op_sel_hi:[1,0,1]
	s_waitcnt lgkmcnt(0)
	v_pk_fma_f32 v[52:53], v[52:53], s[72:73], v[28:29] op_sel_hi:[1,0,1]
	v_pk_fma_f32 v[28:29], v[50:51], s[72:73], v[26:27] op_sel_hi:[1,0,1]
	s_and_b64 vcc, exec, s[6:7]
	s_mov_b64 s[38:39], -1
	v_cvt_pk_bf16_f32 v26, v30, v31
	v_cvt_pk_bf16_f32 v27, v32, v33
	v_cvt_pk_bf16_f32 v28, v28, v29
	v_cvt_pk_bf16_f32 v29, v52, v53
	flat_store_dwordx4 v[76:77], v[26:29]
	s_cbranch_vccnz .LBB0_405
	flat_load_dwordx4 v[30:33], v[76:77] offset:16
	v_mov_b32_e32 v50, v78
	v_mov_b32_e32 v51, v78
	s_mov_b64 s[38:39], 0
	s_waitcnt vmcnt(0) lgkmcnt(0)
	v_lshlrev_b32_e32 v52, 16, v30
	v_and_b32_e32 v53, 0xffff0000, v30
	v_lshlrev_b32_e32 v30, 16, v31
	v_and_b32_e32 v31, 0xffff0000, v31
	v_lshlrev_b32_e32 v54, 16, v32
	v_and_b32_e32 v55, 0xffff0000, v32
	v_lshlrev_b32_e32 v56, 16, v33
	v_and_b32_e32 v57, 0xffff0000, v33
	v_sub_f32_e32 v31, v31, v80
	v_sub_f32_e32 v30, v30, v80
	v_sub_f32_e32 v33, v53, v80
	v_sub_f32_e32 v32, v52, v80
	v_sub_f32_e32 v53, v57, v80
	v_sub_f32_e32 v52, v56, v80
	v_sub_f32_e32 v55, v55, v80
	v_sub_f32_e32 v54, v54, v80
	v_pk_mul_f32 v[32:33], v[78:79], v[32:33]
	v_pk_mul_f32 v[30:31], v[50:51], v[30:31]
	v_pk_mul_f32 v[54:55], v[78:79], v[54:55]
	v_pk_mul_f32 v[56:57], v[50:51], v[52:53]
	v_pk_fma_f32 v[52:53], v[44:45], v[30:31], v[48:49]
	v_pk_fma_f32 v[50:51], v[42:43], v[32:33], v[46:47]
	v_pk_fma_f32 v[32:33], v[36:37], v[56:57], v[40:41]
	v_pk_fma_f32 v[30:31], v[34:35], v[54:55], v[38:39]
.LBB0_405:
	s_andn2_b64 vcc, exec, s[38:39]
	s_cbranch_vccnz .LBB0_407
	s_waitcnt vmcnt(2)
	v_mov_b32_e32 v30, v230
	v_mov_b32_e32 v31, v231
	v_mov_b32_e32 v32, v232
	v_mov_b32_e32 v33, v233
	v_mov_b32_e32 v50, v234
	v_mov_b32_e32 v51, v235
	v_mov_b32_e32 v52, v236
	v_mov_b32_e32 v53, v237
	v_add_u32_e32 v238, 0x20000, v238
	global_load_dwordx4 v[222:225], v238, s[12:13] offset:16
	global_load_dwordx4 v[226:229], v238, s[12:13]
	global_load_dwordx4 v[230:233], v238, s[12:13] offset:48
	global_load_dwordx4 v[234:237], v238, s[12:13] offset:32
.LBB0_407:
	v_and_b32_e32 v79, 16, v26
	v_and_b32_e32 v78, 0xffff0000, v26
	v_lshlrev_b32_e32 v83, 16, v27
	v_lshlrev_b32_e32 v82, 16, v28
	v_and_b32_e32 v80, 0xffff0000, v27
	v_mov_b32_e32 v81, v78
	v_pk_mov_b32 v[84:85], v[82:83], v[78:79] op_sel:[1,0]
	v_and_b32_e32 v54, 0xffff0000, v28
	v_lshlrev_b32_e32 v56, 16, v29
	v_lshlrev_b32_e32 v26, 16, v26
	v_and_b32_e32 v28, 0xffff0000, v29
	v_mov_b32_e32 v29, v80
	v_mov_b32_e32 v55, v83
	v_mov_b32_e32 v27, v80
	v_mov_b32_e32 v57, v80
	v_pk_add_f32 v[86:87], v[80:81], v[84:85]
	v_pk_mul_f32 v[80:81], v[80:81], v[84:85]
	v_pk_add_f32 v[78:79], v[26:27], v[78:79] op_sel_hi:[0,1]
	v_mov_b32_e32 v87, v81
	v_pk_add_f32 v[80:81], v[82:83], v[54:55]
	v_pk_mul_f32 v[84:85], v[82:83], v[82:83]
	v_mov_b32_e32 v55, v28
	v_mul_f32_e32 v79, v26, v26
	v_mov_b32_e32 v81, v85
	v_pk_add_f32 v[84:85], v[28:29], v[56:57]
	v_pk_mul_f32 v[26:27], v[28:29], v[26:27]
	v_mov_b32_e32 v83, v56
	v_pk_mul_f32 v[28:29], v[54:55], v[54:55]
	v_mov_b32_e32 v85, v27
	v_pk_fma_f32 v[28:29], v[82:83], v[82:83], v[28:29]
	v_pk_add_f32 v[78:79], v[78:79], v[86:87]
	v_pk_add_f32 v[26:27], v[80:81], v[84:85]
	v_pk_add_f32 v[28:29], v[28:29], v[28:29] op_sel_hi:[0,1]
	v_pk_add_f32 v[26:27], v[78:79], v[26:27]
	v_mov_b32_e32 v28, v1
	v_pk_fma_f32 v[24:25], v[52:53], s[72:73], v[24:25] op_sel_hi:[1,0,1]
	v_pk_fma_f32 v[22:23], v[50:51], s[72:73], v[22:23] op_sel_hi:[1,0,1]
	v_pk_fma_f32 v[20:21], v[32:33], s[72:73], v[20:21] op_sel_hi:[1,0,1]
	v_pk_fma_f32 v[18:19], v[30:31], s[72:73], v[18:19] op_sel_hi:[1,0,1]
	v_pk_add_f32 v[26:27], v[26:27], v[28:29]
	v_cvt_pk_bf16_f32 v22, v22, v23
	v_cvt_pk_bf16_f32 v23, v24, v25
	v_cvt_pk_bf16_f32 v24, v18, v19
	v_cvt_pk_bf16_f32 v25, v20, v21
	flat_store_dwordx4 v[76:77], v[22:25] offset:16
	v_lshlrev_b32_e32 v18, 16, v22
	v_and_b32_e32 v20, 0xffff0000, v22
	v_lshlrev_b32_e32 v28, 16, v23
	v_and_b32_e32 v30, 0xffff0000, v23
	v_lshlrev_b32_e32 v32, 16, v24
	v_and_b32_e32 v50, 0xffff0000, v24
	v_lshlrev_b32_e32 v52, 16, v25
	v_and_b32_e32 v54, 0xffff0000, v25
	v_mul_f32_e32 v19, v18, v18
	v_mul_f32_e32 v21, v20, v20
	v_mul_f32_e32 v29, v28, v28
	v_mul_f32_e32 v31, v30, v30
	v_mul_f32_e32 v33, v32, v32
	v_mul_f32_e32 v51, v50, v50
	v_mul_f32_e32 v53, v52, v52
	v_mul_f32_e32 v55, v54, v54
	v_pk_add_f32 v[18:19], v[18:19], v[20:21]
	v_pk_add_f32 v[20:21], v[28:29], v[30:31]
	v_pk_add_f32 v[28:29], v[52:53], v[54:55]
	v_pk_add_f32 v[18:19], v[18:19], v[20:21]
	v_pk_add_f32 v[20:21], v[32:33], v[50:51]
	s_nop 0
	v_pk_add_f32 v[20:21], v[20:21], v[28:29]
	s_nop 0
	v_pk_add_f32 v[18:19], v[18:19], v[20:21]
	s_nop 0
	v_pk_add_f32 v[18:19], v[26:27], v[18:19]
	ds_bpermute_b32 v20, v213, v18
	ds_bpermute_b32 v21, v213, v19
	s_waitcnt lgkmcnt(0)
	v_pk_add_f32 v[18:19], v[18:19], v[20:21]
	ds_bpermute_b32 v20, v214, v18
	ds_bpermute_b32 v21, v214, v19
	s_and_saveexec_b64 s[38:39], s[0:1]
	s_cbranch_execz .LBB0_409
	v_lshlrev_b64 v[22:23], 8, v[74:75]
	v_lshl_add_u64 v[22:23], s[10:11], 0, v[22:23]
	v_lshl_add_u64 v[22:23], s[36:37], 3, v[22:23]
	s_waitcnt lgkmcnt(0)
	v_pk_add_f32 v[18:19], v[18:19], v[20:21]
	flat_store_dwordx2 v[22:23], v[18:19]

; __device__ __forceinline__ float bf_lo(unsigned w) { return __uint_as_float(w << 16); }
; __device__ __forceinline__ float bf_hi(unsigned w) { return __uint_as_float(w & 0xffff0000u); }
; __device__ __forceinline__ float shflx(float v, int k, int lane) { return __int_as_float(__builtin_amdgcn_ds_bpermute((lane ^ k) << 2, __float_as_int(v))); }
; __device__ __forceinline__ u32x4 pack8(const f32x4 a, const f32x4 b) { u32x4 w; w.x = cvt_pk_bf16(a[0], a[1]); w.y = cvt_pk_bf16(a[2], a[3]); w.z = cvt_pk_bf16(b[0], b[1]); w.w = cvt_pk_bf16(b[2], b[3]); return w; }
;     __device__ __forceinline__ void operator()(const f32x4 (&acc)[2][2][4][2], const pg8::Unit& u, int wr, int wc, int fr, int fq, LAS unsigned char* lds, int par) const {
;     ...
;                 for (int bj = 0; bj < 2; ++bj) {
;                     f32x4 r0, r1;
;                     if (prev) {
;                         const u32x4 w = *(const u32x4*)(tb + ro + bj * 8);
;                         r0 = (f32x4){bf_lo(w.x), bf_hi(w.x), bf_lo(w.y), bf_hi(w.y)}; r1 = (f32x4){bf_lo(w.z), bf_hi(w.z), bf_lo(w.w), bf_hi(w.w)};
;                         r0 = (r0 - mu) * rstd * gg[2 * bj] + bb[2 * bj]; r1 = (r1 - mu) * rstd * gg[2 * bj + 1] + bb[2 * bj + 1];
;                     } else { r0 = *(const f32x4*)(xin + ro + bj * 8); r1 = *(const f32x4*)(xin + ro + bj * 8 + 4); }
;                     const f32x4 t0 = r0 * ALPHA + acc[ai][bj][m][0], t1 = r1 * ALPHA + acc[ai][bj][m][1];
;                     if (xout != nullptr) { *(f32x4*)(xout + ro + bj * 8) = t0; *(f32x4*)(xout + ro + bj * 8 + 4) = t1; }
;                     const u32x4 pw = pack8(t0, t1);
;                     *(u32x4*)(tb + ro + bj * 8) = pw;
;                     const float a0 = bf_lo(pw.x), a1 = bf_hi(pw.x), a2 = bf_lo(pw.y), a3 = bf_hi(pw.y), a4 = bf_lo(pw.z), a5 = bf_hi(pw.z), a6 = bf_lo(pw.w), a7 = bf_hi(pw.w);
;                     s1 += ((a0 + a1) + (a2 + a3)) + ((a4 + a5) + (a6 + a7));
;                     s2 += ((a0 * a0 + a1 * a1) + (a2 * a2 + a3 * a3)) + ((a4 * a4 + a5 * a5) + (a6 * a6 + a7 * a7));
;                 }
;                 s1 += shflx(s1, 16, fr + 16 * fq); s1 += shflx(s1, 32, fr + 16 * fq); s2 += shflx(s2, 16, fr + 16 * fq); s2 += shflx(s2, 32, fr + 16 * fq);
;                 if (fq == 0) { float* sp = stats_out + ((size_t)row * 32 + u.pn * 4 + wc) * 2; sp[0] = s1; sp[1] = s2; }
.LBB0_414:
	s_andn2_b64 vcc, exec, s[38:39]
	v_lshl_add_u64 v[50:51], v[50:51], 2, s[12:13]
	s_cbranch_vccnz .LBB0_416
	s_waitcnt vmcnt(3)
	v_mov_b32_e32 v22, v222
	v_mov_b32_e32 v23, v223
	v_mov_b32_e32 v24, v224
	v_mov_b32_e32 v25, v225
	v_mov_b32_e32 v18, v226
	v_mov_b32_e32 v19, v227
	v_mov_b32_e32 v20, v228
	v_mov_b32_e32 v21, v229
	s_waitcnt lgkmcnt(0)
.LBB0_416:
	s_waitcnt lgkmcnt(0)
	v_pk_fma_f32 v[16:17], v[20:21], s[72:73], v[16:17] op_sel_hi:[1,0,1]
	v_pk_fma_f32 v[14:15], v[18:19], s[72:73], v[14:15] op_sel_hi:[1,0,1]
	v_pk_fma_f32 v[18:19], v[24:25], s[72:73], v[12:13] op_sel_hi:[1,0,1]
	v_pk_fma_f32 v[12:13], v[22:23], s[72:73], v[10:11] op_sel_hi:[1,0,1]
	s_and_b64 vcc, exec, s[6:7]
	s_mov_b64 s[38:39], -1
	v_cvt_pk_bf16_f32 v10, v14, v15
	v_cvt_pk_bf16_f32 v11, v16, v17
	v_cvt_pk_bf16_f32 v12, v12, v13
	v_cvt_pk_bf16_f32 v13, v18, v19
	flat_store_dwordx4 v[28:29], v[10:13]
	s_cbranch_vccnz .LBB0_418
	flat_load_dwordx4 v[14:17], v[28:29] offset:16
	v_mov_b32_e32 v18, v30
	v_mov_b32_e32 v19, v30
	s_mov_b64 s[38:39], 0
	s_waitcnt vmcnt(0) lgkmcnt(0)
	v_lshlrev_b32_e32 v20, 16, v14
	v_and_b32_e32 v21, 0xffff0000, v14
	v_lshlrev_b32_e32 v14, 16, v15
	v_and_b32_e32 v15, 0xffff0000, v15
	v_lshlrev_b32_e32 v22, 16, v16
	v_and_b32_e32 v23, 0xffff0000, v16
	v_lshlrev_b32_e32 v24, 16, v17
	v_and_b32_e32 v25, 0xffff0000, v17
	v_sub_f32_e32 v15, v15, v32
	v_sub_f32_e32 v14, v14, v32
	v_sub_f32_e32 v17, v21, v32
	v_sub_f32_e32 v16, v20, v32
	v_sub_f32_e32 v21, v25, v32
	v_sub_f32_e32 v20, v24, v32
	v_sub_f32_e32 v23, v23, v32
	v_sub_f32_e32 v22, v22, v32
	v_pk_mul_f32 v[16:17], v[30:31], v[16:17]
	v_pk_mul_f32 v[14:15], v[18:19], v[14:15]
	v_pk_mul_f32 v[22:23], v[30:31], v[22:23]
	v_pk_mul_f32 v[24:25], v[18:19], v[20:21]
	v_pk_fma_f32 v[20:21], v[44:45], v[14:15], v[48:49]
	v_pk_fma_f32 v[18:19], v[42:43], v[16:17], v[46:47]
	v_pk_fma_f32 v[16:17], v[36:37], v[24:25], v[40:41]
	v_pk_fma_f32 v[14:15], v[34:35], v[22:23], v[38:39]
.LBB0_418:
	s_andn2_b64 vcc, exec, s[38:39]
	s_cbranch_vccnz .LBB0_420
	s_waitcnt vmcnt(2)
	v_mov_b32_e32 v14, v230
	v_mov_b32_e32 v15, v231
	v_mov_b32_e32 v16, v232
	v_mov_b32_e32 v17, v233
	v_mov_b32_e32 v18, v234
	v_mov_b32_e32 v19, v235
	v_mov_b32_e32 v20, v236
	v_mov_b32_e32 v21, v237
.LBB0_420:
	v_and_b32_e32 v31, 16, v10
	v_and_b32_e32 v30, 0xffff0000, v10
	v_lshlrev_b32_e32 v35, 16, v11
	v_lshlrev_b32_e32 v34, 16, v12
	v_and_b32_e32 v32, 0xffff0000, v11
	v_mov_b32_e32 v33, v30
	v_pk_mov_b32 v[36:37], v[34:35], v[30:31] op_sel:[1,0]
	v_and_b32_e32 v22, 0xffff0000, v12
	v_lshlrev_b32_e32 v24, 16, v13
	v_lshlrev_b32_e32 v10, 16, v10
	v_and_b32_e32 v12, 0xffff0000, v13
	v_mov_b32_e32 v13, v32
	v_mov_b32_e32 v23, v35
	v_mov_b32_e32 v11, v32
	v_mov_b32_e32 v25, v32
	v_pk_add_f32 v[38:39], v[32:33], v[36:37]
	v_pk_mul_f32 v[32:33], v[32:33], v[36:37]
	v_pk_add_f32 v[30:31], v[10:11], v[30:31] op_sel_hi:[0,1]
	v_mov_b32_e32 v39, v33
	v_pk_add_f32 v[32:33], v[34:35], v[22:23]
	v_pk_mul_f32 v[36:37], v[34:35], v[34:35]
	v_mov_b32_e32 v23, v12
	v_mul_f32_e32 v31, v10, v10
	v_mov_b32_e32 v33, v37
	v_pk_add_f32 v[36:37], v[12:13], v[24:25]
	v_pk_mul_f32 v[10:11], v[12:13], v[10:11]
	v_mov_b32_e32 v35, v24
	v_pk_mul_f32 v[12:13], v[22:23], v[22:23]
	v_mov_b32_e32 v37, v11
	v_pk_fma_f32 v[12:13], v[34:35], v[34:35], v[12:13]
	v_pk_add_f32 v[30:31], v[30:31], v[38:39]
	v_pk_add_f32 v[10:11], v[32:33], v[36:37]
	v_pk_add_f32 v[12:13], v[12:13], v[12:13] op_sel_hi:[0,1]
	v_pk_add_f32 v[10:11], v[30:31], v[10:11]
	v_mov_b32_e32 v12, v1
	v_pk_fma_f32 v[8:9], v[20:21], s[72:73], v[8:9] op_sel_hi:[1,0,1]
	v_pk_fma_f32 v[6:7], v[18:19], s[72:73], v[6:7] op_sel_hi:[1,0,1]
	v_pk_fma_f32 v[4:5], v[16:17], s[72:73], v[4:5] op_sel_hi:[1,0,1]
	v_pk_fma_f32 v[2:3], v[14:15], s[72:73], v[2:3] op_sel_hi:[1,0,1]
	v_pk_add_f32 v[10:11], v[10:11], v[12:13]
	v_cvt_pk_bf16_f32 v6, v6, v7
	v_cvt_pk_bf16_f32 v7, v8, v9
	v_cvt_pk_bf16_f32 v8, v2, v3
	v_cvt_pk_bf16_f32 v9, v4, v5
	flat_store_dwordx4 v[28:29], v[6:9] offset:16
	v_lshlrev_b32_e32 v2, 16, v6
	v_and_b32_e32 v4, 0xffff0000, v6
	v_lshlrev_b32_e32 v12, 16, v7
	v_and_b32_e32 v14, 0xffff0000, v7
	v_lshlrev_b32_e32 v16, 16, v8
	v_and_b32_e32 v18, 0xffff0000, v8
	v_lshlrev_b32_e32 v20, 16, v9
	v_and_b32_e32 v22, 0xffff0000, v9
	v_mul_f32_e32 v3, v2, v2
	v_mul_f32_e32 v5, v4, v4
	v_mul_f32_e32 v13, v12, v12
	v_mul_f32_e32 v15, v14, v14
	v_mul_f32_e32 v17, v16, v16
	v_mul_f32_e32 v19, v18, v18
	v_mul_f32_e32 v21, v20, v20
	v_mul_f32_e32 v23, v22, v22
	v_pk_add_f32 v[2:3], v[2:3], v[4:5]
	v_pk_add_f32 v[4:5], v[12:13], v[14:15]
	v_pk_add_f32 v[12:13], v[20:21], v[22:23]
	v_pk_add_f32 v[2:3], v[2:3], v[4:5]
	v_pk_add_f32 v[4:5], v[16:17], v[18:19]
	s_nop 0
	v_pk_add_f32 v[4:5], v[4:5], v[12:13]
	s_nop 0
	v_pk_add_f32 v[2:3], v[2:3], v[4:5]
	s_nop 0
	v_pk_add_f32 v[2:3], v[10:11], v[2:3]
	ds_bpermute_b32 v4, v213, v2
	ds_bpermute_b32 v5, v213, v3
	s_waitcnt lgkmcnt(0)
	v_pk_add_f32 v[2:3], v[2:3], v[4:5]
	ds_bpermute_b32 v4, v214, v2
	ds_bpermute_b32 v5, v214, v3
	s_and_saveexec_b64 s[38:39], s[0:1]
	s_cbranch_execz .LBB0_422
	v_lshlrev_b64 v[6:7], 8, v[26:27]
	v_lshl_add_u64 v[6:7], s[10:11], 0, v[6:7]
	v_lshl_add_u64 v[6:7], s[36:37], 3, v[6:7]
	s_waitcnt lgkmcnt(0)
	v_pk_add_f32 v[2:3], v[2:3], v[4:5]
	flat_store_dwordx2 v[6:7], v[2:3]
